# GEMM K-loops: per-phase s_setprio flips deleted (no replacement), one static s_setprio 1 for waves 4-7 at kernel start
# speedup vs baseline: 1.0105x; 1.0017x over previous
; __device__ __forceinline__ unsigned xcc_id() { return (unsigned)__builtin_amdgcn_s_getreg((3 << 11) | 20) & 0xFu; }
; __global__ void __launch_bounds__(NWAVES * 64, 2) fwd_megakernel(Args args) {
;     ...
;     unsigned char* ws = args.ws;
;     const float* x_in = args.in[I_X];
;     float* xres = args.out;
;     bf16* XN = (bf16*)(ws + WS_XN); bf16* QKV = (bf16*)(ws + WS_QKV); bf16* AO = (bf16*)(ws + WS_AO); bf16* HB = (bf16*)(ws + WS_HB);
;     int* SEL = (int*)(ws + WS_SEL); float* SC = (float*)(ws + WS_SC);
;     const int lo = args.ph_lo, hi = args.ph_hi;
;     int ph = 0;
;     unsigned* bar_ctr = (unsigned*)ws; unsigned bar_target = 0u; const unsigned bar_xcc = xcc_id(); unsigned bar_gsz = 1u, bar_nx = 1u;
.LBB0_115:
	s_nop 0
	v_readlane_b32 s60, v251, 8
	v_readlane_b32 s62, v251, 10
	v_readlane_b32 s63, v251, 11
	s_add_u32 s76, s62, 0x17300000
	s_addc_u32 s77, s63, 0
	s_add_u32 s78, s62, 0x2c300000
	s_addc_u32 s79, s63, 0
	s_add_u32 s67, s62, 0x38300000
	s_addc_u32 s85, s63, 0
	s_add_u32 s0, s62, 0x1b300000
	s_addc_u32 s1, s63, 0
	v_readlane_b32 s61, v251, 9
	v_writelane_b32 v251, s0, 19
	s_waitcnt vmcnt(30)
	v_lshrrev_b32_e32 v1, 20, v0
	v_lshrrev_b32_e32 v0, 10, v0
	v_writelane_b32 v251, s1, 20
	s_add_u32 s0, s62, 0x1c300000
	s_addc_u32 s1, s63, 0
	v_writelane_b32 v251, s0, 21
	v_or_b32_e32 v0, v0, v1
	v_mbcnt_hi_u32_b32 v206, -1, v39
	v_writelane_b32 v251, s1, 22
	s_add_u32 s0, s62, 0x3c300000
	v_writelane_b32 v251, s0, 23
	s_addc_u32 s0, s63, 0
	v_writelane_b32 v251, s0, 24
	s_add_u32 s0, s62, 0x4100000
	v_writelane_b32 v251, s0, 25
	s_addc_u32 s0, s63, 0
	v_writelane_b32 v251, s0, 26
	s_and_b32 s1, s14, 0xffffffc0
	v_readlane_b32 s57, v251, 14
	s_cmpk_lt_i32 s57, 0x440
	s_cselect_b64 s[2:3], -1, 0
	s_ashr_i32 s86, s57, 31
	s_lshr_b32 s0, s86, 29
	v_writelane_b32 v251, s2, 27
	s_add_i32 s0, s57, s0
	s_ashr_i32 s87, s64, 31
	v_writelane_b32 v251, s3, 28
	s_ashr_i32 s3, s0, 3
	s_and_b32 s0, s0, -8
	s_sub_i32 s2, s57, s0
	s_add_u32 s0, s62, 0x100000
	v_writelane_b32 v251, s0, 29
	s_addc_u32 s0, s63, 0
	s_cmpk_lt_i32 s57, 0x600
	v_writelane_b32 v251, s0, 30
	s_cselect_b64 s[4:5], -1, 0
	v_writelane_b32 v251, s4, 31
	s_lshl_b32 s0, s12, 8
	v_mov_b32_e32 v183, 0
	v_writelane_b32 v251, s5, 32
	s_add_u32 s4, s62, s0
	s_addc_u32 s5, s63, 0
	s_add_u32 s16, s4, 0x2900
	v_writelane_b32 v251, s4, 33
	s_addc_u32 s17, s5, 0
	s_cmp_lt_u32 s14, 64
	v_writelane_b32 v251, s5, 34
	s_cselect_b64 s[4:5], -1, 0
	s_and_b32 s0, s64, 7
	v_writelane_b32 v251, s4, 35
	s_cmp_lg_u32 s0, 0
	v_mov_b32_e32 v208, 0x358637bd
	v_writelane_b32 v251, s5, 36
	s_cselect_b64 s[4:5], -1, 0
	v_writelane_b32 v251, s4, 37
	s_cmp_lt_i32 s66, 0x10000
	v_mov_b32_e32 v209, 0x260
	v_writelane_b32 v251, s5, 38
	s_cselect_b64 s[4:5], -1, 0
	v_writelane_b32 v251, s4, 39
	s_and_b32 s0, s57, 4
	v_mov_b32_e32 v210, 1
	v_writelane_b32 v251, s5, 40
	v_writelane_b32 v251, s0, 41
	s_and_b32 s0, s57, -8
	s_add_i32 s0, s13, s0
	s_cmpk_lt_i32 s0, 0x2000
	v_writelane_b32 v251, s0, 42
	s_cselect_b64 s[4:5], -1, 0
	v_writelane_b32 v251, s4, 43
	s_and_b32 s0, s57, 3
	v_mov_b32_e32 v211, 0x3e0293ee
	v_writelane_b32 v251, s5, 44
	s_lshl_b32 s4, s0, 7
	v_writelane_b32 v251, s4, 45
	s_lshl_b32 s4, s0, 9
	v_readlane_b32 s65, v251, 16
	v_writelane_b32 v251, s4, 46
	s_add_i32 s4, s65, s4
	s_lshl_b32 s0, s0, 10
	v_writelane_b32 v251, s4, 47
	s_add_u32 s4, s67, s0
	s_addc_u32 s5, s85, 0
	v_writelane_b32 v251, s4, 48
	s_cmpk_lt_i32 s66, 0x2000
	v_mov_b32_e32 v212, 0x2200
	v_writelane_b32 v251, s5, 49
	s_cselect_b64 s[4:5], -1, 0
	v_writelane_b32 v251, s4, 50
	s_cmpk_lt_i32 s57, 0x200
	v_mov_b32_e32 v213, 0xff800000
	v_writelane_b32 v251, s5, 51
	s_cselect_b64 s[4:5], -1, 0
	v_writelane_b32 v251, s4, 52
	s_lshl_b32 s0, s2, 6
	v_mov_b64_e32 v[184:185], 0x200
	v_writelane_b32 v251, s5, 53
	v_mov_b64_e32 v[186:187], 0x1ff
	v_readlane_b32 s4, v251, 0
	v_readlane_b32 s6, v251, 2
	v_readlane_b32 s7, v251, 3
	s_cmp_lg_u64 s[6:7], 0
	s_cselect_b64 s[88:89], -1, 0
	s_add_u32 s4, s62, 0x7300000
	v_readlane_b32 s5, v251, 1
	v_readlane_b32 s8, v251, 4
	v_readlane_b32 s9, v251, 5
	v_readlane_b32 s10, v251, 6
	v_readlane_b32 s11, v251, 7
	v_writelane_b32 v251, s4, 54
	s_addc_u32 s4, s63, 0
	s_cmpk_lt_i32 s57, 0x800
	v_writelane_b32 v251, s4, 55
	s_cselect_b64 s[4:5], -1, 0
	v_writelane_b32 v251, s4, 56
	s_movk_i32 s7, 0x89
	s_mul_i32 s6, s2, 0x101
	v_writelane_b32 v251, s5, 57
	s_lshl_b32 s4, s2, 8
	s_add_u32 s5, s62, 0xf300000
	v_writelane_b32 v251, s5, 58
	s_addc_u32 s5, s63, 0
	s_cmp_lt_i32 s2, 0
	s_cselect_b32 s7, s7, 0x88
	v_writelane_b32 v251, s5, 59
	s_mul_i32 s5, s2, 0x41
	s_mul_i32 s7, s2, s7
	s_movk_i32 s8, 0xc1
	s_cselect_b32 s8, s8, 0xc0
	s_cselect_b32 s5, s5, s0
	s_cselect_b32 s4, s6, s4
	s_add_i32 s7, s7, s3
	s_mul_hi_i32 s0, s7, 0x78787879
	s_lshr_b32 s6, s0, 31
	s_ashr_i32 s0, s0, 6
	s_add_i32 s0, s0, s6
	s_mul_i32 s6, s0, 0x88
	s_sub_i32 s6, s7, s6
	s_lshl_b32 s9, s0, 3
	s_bfe_u32 s0, s6, 0x3001c
	s_add_i32 s7, s6, s0
	s_sext_i32_i16 s10, s7
	s_and_b32 s7, s7, 0xfff8
	s_sub_i32 s6, s6, s7
	s_sext_i32_i16 s6, s6
	s_mul_i32 s2, s2, s8
	s_add_i32 s14, s9, s6
	s_ashr_i32 s6, s10, 3
	s_add_i32 s2, s2, s3
	v_writelane_b32 v251, s6, 60
	s_mul_hi_i32 s6, s2, 0x2aaaaaab
	s_lshr_b32 s7, s6, 31
	s_ashr_i32 s6, s6, 5
	s_add_i32 s6, s6, s7
	s_mul_i32 s7, s6, 0xc0
	s_sub_i32 s7, s2, s7
	s_bfe_u32 s2, s7, 0x3001c
	s_add_i32 s8, s7, s2
	s_sext_i32_i16 s9, s8
	s_and_b32 s8, s8, 0xfff8
	s_sub_i32 s7, s7, s8
	s_lshl_b32 s6, s6, 3
	s_sext_i32_i16 s7, s7
	s_lshr_b32 s0, s10, 3
	s_lshr_b32 s2, s9, 3
	s_add_i32 s10, s6, s7
	s_ashr_i32 s6, s9, 3
	v_writelane_b32 v251, s6, 61
	s_add_u32 s6, s62, 0x1100
	s_addc_u32 s7, s63, 0
	v_writelane_b32 v251, s6, 62
	s_cmp_eq_u32 s12, 0
	v_mov_b64_e32 v[234:235], 0x7ff
	v_writelane_b32 v251, s7, 63
	s_cselect_b64 s[6:7], -1, 0
	v_writelane_b32 v252, s6, 0
	s_movk_i32 s90, 0x2000
	s_mov_b32 s49, 1
	v_writelane_b32 v252, s7, 1
	s_add_u32 s6, s62, 0x1200
	s_addc_u32 s7, s63, 0
	v_writelane_b32 v252, s6, 2
	s_cmp_eq_u32 s12, 1
	s_mov_b32 s33, 0xf800000
	v_writelane_b32 v252, s7, 3
	s_cselect_b64 s[6:7], -1, 0
	v_writelane_b32 v252, s6, 4
	s_movk_i32 s91, 0x2200
	s_movk_i32 s92, 0x3000
	v_writelane_b32 v252, s7, 5
	s_add_u32 s6, s62, 0x1300
	s_addc_u32 s7, s63, 0
	v_writelane_b32 v252, s6, 6
	s_cmp_eq_u32 s12, 2
	s_movk_i32 s93, 0x5a
	v_writelane_b32 v252, s7, 7
	s_cselect_b64 s[6:7], -1, 0
; __device__ __forceinline__ unsigned xcc_id() { return (unsigned)__builtin_amdgcn_s_getreg((3 << 11) | 20) & 0xFu; }
; template <class Epi, class Sched, bool ALIGN_EPI = false, bool SP2 = false>
; __device__ __forceinline__ void gemm_phase(PG8_LAS unsigned char* lds, const Gemm g, const Sched& S, const Epi& E, const int wid_in) {
;     int tid_ = (wid_in << 6) | __builtin_amdgcn_mbcnt_hi(~0u, __builtin_amdgcn_mbcnt_lo(~0u, 0u)); asm volatile("" : "+v"(tid_)); const int tid = tid_, wid = __builtin_amdgcn_readfirstlane(tid >> 6), lane = tid & 63, wr = wid >> 2, wc = wid & 3, fr = lane & 15, fq = lane >> 4;
; __global__ void __launch_bounds__(NWAVES * 64, 2) fwd_megakernel(Args args) {
;     ...
;     unsigned* bar_ctr = (unsigned*)ws; unsigned bar_target = 0u; const unsigned bar_xcc = xcc_id(); unsigned bar_gsz = 1u, bar_nx = 1u;
	v_writelane_b32 v252, s6, 8
	s_mov_b32 s94, 0xff800000
	s_mov_b32 s73, 0
	v_writelane_b32 v252, s7, 9
	s_add_u32 s6, s62, 0x1400
	s_addc_u32 s7, s63, 0
	v_writelane_b32 v252, s6, 10
	s_cmp_eq_u32 s12, 3
	s_mov_b64 s[96:97], 0x2000
	v_writelane_b32 v252, s7, 11
	s_cselect_b64 s[6:7], -1, 0
	v_writelane_b32 v252, s6, 12
	s_mov_b64 s[74:75], 0x80
	s_nop 0
	v_writelane_b32 v252, s7, 13
	s_add_u32 s6, s62, 0x1500
	s_addc_u32 s7, s63, 0
	v_writelane_b32 v252, s6, 14
	s_cmp_eq_u32 s12, 4
	s_nop 0
	v_writelane_b32 v252, s7, 15
	s_cselect_b64 s[6:7], -1, 0
	v_writelane_b32 v252, s6, 16
	s_nop 1
	v_writelane_b32 v252, s7, 17
	s_add_u32 s6, s62, 0x1600
	s_addc_u32 s7, s63, 0
	v_writelane_b32 v252, s6, 18
	s_cmp_eq_u32 s12, 5
	s_nop 0
	v_writelane_b32 v252, s7, 19
	s_cselect_b64 s[6:7], -1, 0
	v_writelane_b32 v252, s6, 20
	s_nop 1
	v_writelane_b32 v252, s7, 21
	s_add_u32 s6, s62, 0x1700
	s_addc_u32 s7, s63, 0
	v_writelane_b32 v252, s6, 22
	s_cmp_eq_u32 s12, 6
	s_nop 0
	v_writelane_b32 v252, s7, 23
	s_cselect_b64 s[6:7], -1, 0
	v_writelane_b32 v252, s6, 24
	s_nop 1
	v_writelane_b32 v252, s7, 25
	s_add_u32 s6, s62, 0x1800
	s_addc_u32 s7, s63, 0
	v_writelane_b32 v252, s6, 26
	s_cmp_eq_u32 s12, 7
	s_nop 0
	v_writelane_b32 v252, s7, 27
	s_cselect_b64 s[6:7], -1, 0
	v_writelane_b32 v252, s6, 28
	s_nop 1
	v_writelane_b32 v252, s7, 29
	s_add_u32 s6, s62, 0x1900
	s_addc_u32 s7, s63, 0
	v_writelane_b32 v252, s6, 30
	s_cmp_eq_u32 s12, 8
	s_nop 0
	v_writelane_b32 v252, s7, 31
	s_cselect_b64 s[6:7], -1, 0
	v_writelane_b32 v252, s6, 32
	s_nop 1
	v_writelane_b32 v252, s7, 33
	s_add_u32 s6, s62, 0x1a00
	s_addc_u32 s7, s63, 0
	v_writelane_b32 v252, s6, 34
	s_cmp_eq_u32 s12, 9
	s_nop 0
	v_writelane_b32 v252, s7, 35
	s_cselect_b64 s[6:7], -1, 0
	v_writelane_b32 v252, s6, 36
	s_nop 1
	v_writelane_b32 v252, s7, 37
	s_add_u32 s6, s62, 0x1b00
	s_addc_u32 s7, s63, 0
	v_writelane_b32 v252, s6, 38
	s_cmp_eq_u32 s12, 10
	s_nop 0
	v_writelane_b32 v252, s7, 39
	s_cselect_b64 s[6:7], -1, 0
	v_writelane_b32 v252, s6, 40
	s_nop 1
	v_writelane_b32 v252, s7, 41
	s_add_u32 s6, s62, 0x1c00
	s_addc_u32 s7, s63, 0
	v_writelane_b32 v252, s6, 42
	s_cmp_eq_u32 s12, 11
	s_nop 0
	v_writelane_b32 v252, s7, 43
	s_cselect_b64 s[6:7], -1, 0
	v_writelane_b32 v252, s6, 44
	s_nop 1
	v_writelane_b32 v252, s7, 45
	s_add_u32 s6, s62, 0x1d00
	s_addc_u32 s7, s63, 0
	v_writelane_b32 v252, s6, 46
	s_cmp_eq_u32 s12, 12
	s_nop 0
	v_writelane_b32 v252, s7, 47
	s_cselect_b64 s[6:7], -1, 0
	v_writelane_b32 v252, s6, 48
	s_nop 1
	v_writelane_b32 v252, s7, 49
	s_add_u32 s6, s62, 0x1e00
	s_addc_u32 s7, s63, 0
	v_writelane_b32 v252, s6, 50
	s_cmp_eq_u32 s12, 13
	s_nop 0
	v_writelane_b32 v252, s7, 51
	s_cselect_b64 s[6:7], -1, 0
	v_writelane_b32 v252, s6, 52
	s_nop 1
	v_writelane_b32 v252, s7, 53
	s_add_u32 s6, s62, 0x1f00
	s_addc_u32 s7, s63, 0
	v_writelane_b32 v252, s6, 54
	s_cmp_eq_u32 s12, 14
	s_nop 0
	v_writelane_b32 v252, s7, 55
	s_cselect_b64 s[6:7], -1, 0
	v_writelane_b32 v252, s6, 56
	s_nop 1
	v_writelane_b32 v252, s7, 57
	s_add_u32 s6, s62, 0x2000
	s_addc_u32 s7, s63, 0
	v_writelane_b32 v252, s6, 58
	s_cmp_eq_u32 s12, 15
	s_nop 0
	v_writelane_b32 v252, s7, 59
	s_cselect_b64 s[6:7], -1, 0
	v_writelane_b32 v252, s6, 60
	s_add_i32 s5, s5, s3
	s_add_i32 s3, s4, s3
	v_writelane_b32 v252, s7, 61
	s_ashr_i32 s6, s5, 31
	s_lshr_b32 s6, s6, 26
	s_add_i32 s6, s5, s6
	s_and_b32 s7, s6, 0xffc0
	s_sub_i32 s5, s5, s7
	s_bfe_i32 s7, s5, 0x80000
	s_bfe_u32 s7, s7, 0x3000c
	s_ashr_i32 s4, s3, 31
	s_add_i32 s7, s5, s7
	s_lshr_b32 s4, s4, 24
	s_and_b32 s8, s7, 0xf8
	s_add_i32 s4, s3, s4
	s_sub_i32 s5, s5, s8
	s_and_b32 s8, s4, 0xff00
	s_sub_i32 s3, s3, s8
	s_sext_i32_i16 s8, s3
	s_bfe_u32 s8, s8, 0x3001c
	s_add_i32 s8, s3, s8
	s_and_b32 s9, s8, 0xfff8
	s_ashr_i32 s6, s6, 6
	s_sub_i32 s3, s3, s9
	s_lshl_b32 s6, s6, 3
	s_sext_i32_i8 s5, s5
	s_ashr_i32 s4, s4, 8
	s_add_i32 s12, s6, s5
	s_lshl_b32 s4, s4, 3
	s_sext_i32_i16 s5, s8
	s_sext_i32_i16 s3, s3
	s_add_i32 s8, s4, s3
	s_lshr_b32 s4, s5, 3
	s_bfe_i32 s7, s7, 0x80000
	s_ashr_i32 s3, s5, 3
	s_bfe_i64 s[4:5], s[4:5], 0x100000
	s_sext_i32_i16 s7, s7
	v_writelane_b32 v252, s3, 62
	s_lshl_b64 s[4:5], s[4:5], 20
	v_writelane_b32 v252, s4, 63
	s_ashr_i32 s3, s7, 3
	s_mov_b32 s6, s8
	v_writelane_b32 v253, s5, 0
	v_writelane_b32 v253, s3, 1
	s_ashr_i32 s9, s8, 31
	s_lshr_b32 s4, s7, 3
	v_writelane_b32 v253, s6, 2
	s_nop 1
	v_writelane_b32 v253, s7, 3
	s_lshl_b64 s[6:7], s[8:9], 20
	s_add_u32 s6, s76, s6
	s_addc_u32 s7, s77, s7
	s_add_u32 s8, s6, 0x80000
	v_writelane_b32 v253, s6, 4
	s_addc_u32 s9, s7, 0
	s_ashr_i32 s15, s14, 31
	v_writelane_b32 v253, s7, 5
	v_writelane_b32 v253, s8, 6
	s_bfe_i64 s[6:7], s[0:1], 0x100000
	s_lshl_b64 s[6:7], s[6:7], 20
	v_writelane_b32 v253, s9, 7
	v_writelane_b32 v253, s6, 8
	s_mov_b32 s0, s14
	s_nop 0
	v_writelane_b32 v253, s7, 9
	s_lshl_b64 s[6:7], s[14:15], 20
	v_writelane_b32 v253, s0, 10
	s_add_u32 s6, s76, s6
	s_addc_u32 s7, s77, s7
	v_writelane_b32 v253, s1, 11
	s_add_u32 s8, s6, 0x80000
	v_writelane_b32 v253, s6, 12
	s_addc_u32 s9, s7, 0
	s_bfe_i64 s[2:3], s[2:3], 0x100000
	v_writelane_b32 v253, s7, 13
	v_writelane_b32 v253, s8, 14
	s_lshl_b64 s[2:3], s[2:3], 20
	s_ashr_i32 s11, s10, 31
	v_writelane_b32 v253, s9, 15
	v_writelane_b32 v253, s2, 16
	s_mov_b32 s0, s10
	s_nop 0
	v_writelane_b32 v253, s3, 17
	s_lshl_b64 s[2:3], s[10:11], 20
	v_writelane_b32 v253, s0, 18
	s_add_u32 s2, s76, s2
	s_addc_u32 s3, s77, s3
	v_writelane_b32 v253, s1, 19
	s_add_u32 s6, s2, 0x80000
	v_writelane_b32 v253, s2, 20
	s_addc_u32 s7, s3, 0
	s_ashr_i32 s13, s12, 31
	v_writelane_b32 v253, s3, 21
	v_writelane_b32 v253, s6, 22
	s_bfe_i64 s[2:3], s[4:5], 0x100000
	s_lshl_b64 s[4:5], s[12:13], 20
	v_writelane_b32 v253, s7, 23
	s_lshl_b64 s[6:7], s[2:3], 20
	v_writelane_b32 v253, s6, 24
	s_add_u32 s4, s67, s4
	s_addc_u32 s5, s85, s5
	v_writelane_b32 v253, s7, 25
	s_add_u32 s6, s4, 0x80000
	v_writelane_b32 v253, s4, 26
	s_addc_u32 s7, s5, 0
	s_lshl_b64 s[2:3], s[2:3], 22
	v_writelane_b32 v253, s5, 27
	v_writelane_b32 v253, s6, 28
	s_mov_b32 s0, s12
	s_nop 0
	v_writelane_b32 v253, s7, 29
	v_writelane_b32 v253, s2, 30
	s_mov_b32 s6, 0
	s_nop 0
	v_writelane_b32 v253, s3, 31
	s_lshl_b64 s[2:3], s[12:13], 22
	v_writelane_b32 v253, s0, 32
	s_add_u32 s2, s78, s2
	s_addc_u32 s3, s79, s3
	v_writelane_b32 v253, s1, 33
	s_movk_i32 s0, 0x3ff
	v_and_or_b32 v0, v0, s0, v38
	s_add_u32 s0, s2, 0x200000
	v_writelane_b32 v253, s2, 34
	v_or_b32_e32 v207, s1, v206
	s_addc_u32 s1, s3, 0
	v_writelane_b32 v253, s3, 35
	v_writelane_b32 v253, s0, 36
	s_nop 1
	v_writelane_b32 v253, s1, 37
	v_cmp_eq_u32_e64 s[0:1], 0, v38
	s_nop 1
	v_writelane_b32 v253, s0, 38
	s_nop 1
	v_writelane_b32 v253, s1, 39
	v_readfirstlane_b32 s0, v207
	s_nop 3
	s_cmpk_lt_u32 s0, 0x100
	s_cbranch_scc1 .Lprio_skip
	s_setprio 1
; __device__ __forceinline__ unsigned xcc_id() { return (unsigned)__builtin_amdgcn_s_getreg((3 << 11) | 20) & 0xFu; }
; __global__ void __launch_bounds__(NWAVES * 64, 2) fwd_megakernel(Args args) {
;     ...
;     unsigned* bar_ctr = (unsigned*)ws; unsigned bar_target = 0u; const unsigned bar_xcc = xcc_id(); unsigned bar_gsz = 1u, bar_nx = 1u;
.Lprio_skip:
	v_cmp_eq_u32_e64 s[0:1], 0, v0
	s_nop 1
	v_writelane_b32 v253, s0, 40
	s_nop 1
	v_writelane_b32 v253, s1, 41
	v_writelane_b32 v253, s16, 42
	s_nop 1
	v_writelane_b32 v253, s17, 43
	v_writelane_b32 v253, s58, 44
	s_nop 1
	v_writelane_b32 v253, s59, 45
	v_writelane_b32 v253, s64, 46
	v_writelane_b32 v253, s66, 47
	s_nop 1
	v_writelane_b32 v253, s67, 48
	v_writelane_b32 v253, s84, 49
	s_nop 1
	v_writelane_b32 v253, s85, 50
	v_writelane_b32 v253, s76, 51
	s_nop 1
	v_writelane_b32 v253, s77, 52
	v_writelane_b32 v253, s78, 53
	s_nop 1
	v_writelane_b32 v253, s79, 54
	v_writelane_b32 v253, s67, 55
	v_writelane_b32 v253, s85, 56
	v_writelane_b32 v253, s86, 57
	v_writelane_b32 v253, s87, 58
	v_writelane_b32 v253, s88, 59
	s_nop 1
	v_writelane_b32 v253, s89, 60
	s_branch .LBB0_120

; #define PG8_STAGE(bufoff, gbase, voff) do { _Pragma("unroll") for (int _i = 0; _i < 2; ++_i) \
;         __builtin_amdgcn_global_load_lds((const unsigned*)((const char*)(gbase) + (voff)[_i]), (PG8_LAS unsigned*)(lds + (bufoff) + ldsw + _i * 8192), 16, 0, 0); } while (0)
; #define PG8_LDA(dst, b, h) do { _Pragma("unroll") for (int m = 0; m < 4; ++m) _Pragma("unroll") for (int k = 0; k < 2; ++k) dst[m][k] = *(const PG8_LAS bf16x8*)(lds + PG8_SA(b, h) + aoff + m * 2048 + k * 1024); } while (0)
; #define PG8_LDB(dst, b, h) do { _Pragma("unroll") for (int n = 0; n < 2; ++n) _Pragma("unroll") for (int k = 0; k < 2; ++k) dst[n][k] = *(const PG8_LAS bf16x8*)(lds + PG8_SB(b, h) + boff + n * 2048 + k * 1024); } while (0)
; #define PG8_MMA(ai, bj, At, Bt) do { __builtin_amdgcn_s_setprio(1); _Pragma("unroll") for (int m = 0; m < 4; ++m) _Pragma("unroll") for (int n = 0; n < 2; ++n) _Pragma("unroll") for (int k = 0; k < 2; ++k) \
;         acc[ai][bj][m][n] = __builtin_amdgcn_mfma_f32_16x16x32_bf16(Bt[n][k], At[m][k], acc[ai][bj][m][n], 0, 0, 0); __builtin_amdgcn_s_setprio(0); } while (0)
; #define PG8_WAIT_V(n) asm volatile("s_waitcnt vmcnt(" #n ")" ::: "memory")
; #define PG8_WAIT_L(n) asm volatile("s_waitcnt lgkmcnt(" #n ")" ::: "memory")
; #define PG8_BAR __builtin_amdgcn_s_barrier()
; #define PG8_SCHED __builtin_amdgcn_sched_barrier(0)
; template <class Epi, class Sched, bool ALIGN_EPI = false, bool SP2 = false>
; __device__ __forceinline__ void gemm_phase(PG8_LAS unsigned char* lds, const Gemm g, const Sched& S, const Epi& E, const int wid_in) {
;     ...
;             PG8_LDB(B0, 0, 0); PG8_LDB(B1, 0, 1); PG8_SCHED; PG8_LDA(At, 0, 0); PG8_STAGE(PG8_SA(1, 1), a1 + hstep, voffA);
;             PG8_WAIT_V(8); PG8_WAIT_L(0); PG8_BAR; PG8_MMA(0, 0, At, B0); PG8_MMA(0, 1, At, B1); PG8_BAR; PG8_SCHED;
;             PG8_LDA(At, 0, 1); PG8_STAGE(PG8_SB(0, 0), b2, voffB); PG8_STAGE(PG8_SB(0, 1), b2 + hstep, voffB); PG8_STAGE(PG8_SA(0, 0), a2, voffA);
;             PG8_WAIT_V(8); PG8_WAIT_L(0); PG8_BAR; PG8_MMA(1, 0, At, B0); PG8_MMA(1, 1, At, B1); PG8_BAR; PG8_SCHED;
.LBB0_133:
	s_add_u32 s6, s4, 0xfff80080
	s_addc_u32 s7, s5, -1
	s_add_i32 s45, 0, 0x10000
	s_cmp_eq_u32 s44, 28
	s_cselect_b32 s25, s19, s7
	s_cselect_b32 s24, s40, s6
	v_add_u32_e32 v142, s45, v147
	s_cselect_b32 s7, s17, s43
	s_cselect_b32 s6, s41, s42
	s_add_i32 s48, 0, 0x14000
	ds_read_b128 v[138:141], v142
	ds_read_b128 v[150:153], v142 offset:1024
	ds_read_b128 v[154:157], v142 offset:2048
	ds_read_b128 v[158:161], v142 offset:3072
	v_add_u32_e32 v142, s48, v147
	ds_read_b128 v[162:165], v142
	ds_read_b128 v[166:169], v142 offset:1024
	ds_read_b128 v[170:173], v142 offset:2048
	ds_read_b128 v[174:177], v142 offset:3072
	v_lshl_add_u64 v[142:143], s[4:5], 0, v[134:135]
	s_add_i32 m0, s29, 0xc000
	ds_read_b128 v[178:181], v149
	ds_read_b128 v[190:193], v149 offset:1024
	ds_read_b128 v[194:197], v149 offset:2048
	ds_read_b128 v[198:201], v149 offset:3072
	ds_read_b128 v[202:205], v149 offset:4096
	ds_read_b128 v[214:217], v149 offset:5120
	ds_read_b128 v[218:221], v149 offset:6144
	ds_read_b128 v[222:225], v149 offset:7168
	global_load_lds_dwordx4 v[142:143], off
	v_lshl_add_u64 v[142:143], s[4:5], 0, v[136:137]
	s_add_i32 m0, s29, 0xe000
	s_nop 0
	global_load_lds_dwordx4 v[142:143], off
	s_waitcnt vmcnt(8)
	s_waitcnt lgkmcnt(0)
	s_barrier
	s_waitcnt lgkmcnt(0)
	v_mfma_f32_16x16x32_bf16 v[124:127], v[138:141], v[178:181], v[124:127]
	v_mfma_f32_16x16x32_bf16 v[120:123], v[154:157], v[178:181], v[120:123]
	v_mfma_f32_16x16x32_bf16 v[108:111], v[138:141], v[194:197], v[108:111]
	v_mfma_f32_16x16x32_bf16 v[104:107], v[154:157], v[194:197], v[104:107]
	v_mfma_f32_16x16x32_bf16 v[92:95], v[138:141], v[202:205], v[92:95]
	v_mfma_f32_16x16x32_bf16 v[88:91], v[154:157], v[202:205], v[88:91]
	v_mfma_f32_16x16x32_bf16 v[76:79], v[138:141], v[218:221], v[76:79]
	v_mfma_f32_16x16x32_bf16 v[72:75], v[154:157], v[218:221], v[72:75]
	v_mfma_f32_16x16x32_bf16 v[124:127], v[150:153], v[190:193], v[124:127]
	v_mfma_f32_16x16x32_bf16 v[120:123], v[158:161], v[190:193], v[120:123]
	v_mfma_f32_16x16x32_bf16 v[108:111], v[150:153], v[198:201], v[108:111]
	v_mfma_f32_16x16x32_bf16 v[104:107], v[158:161], v[198:201], v[104:107]
	v_mfma_f32_16x16x32_bf16 v[92:95], v[150:153], v[214:217], v[92:95]
	v_mfma_f32_16x16x32_bf16 v[88:91], v[158:161], v[214:217], v[88:91]
	v_mfma_f32_16x16x32_bf16 v[76:79], v[150:153], v[222:225], v[76:79]
	v_mfma_f32_16x16x32_bf16 v[72:75], v[158:161], v[222:225], v[72:75]
	v_mfma_f32_16x16x32_bf16 v[116:119], v[162:165], v[178:181], v[116:119]
	v_mfma_f32_16x16x32_bf16 v[112:115], v[170:173], v[178:181], v[112:115]
	v_mfma_f32_16x16x32_bf16 v[100:103], v[162:165], v[194:197], v[100:103]
	v_mfma_f32_16x16x32_bf16 v[96:99], v[170:173], v[194:197], v[96:99]
	v_mfma_f32_16x16x32_bf16 v[84:87], v[162:165], v[202:205], v[84:87]
	v_mfma_f32_16x16x32_bf16 v[80:83], v[170:173], v[202:205], v[80:83]
	v_mfma_f32_16x16x32_bf16 v[68:71], v[162:165], v[218:221], v[68:71]
	v_mfma_f32_16x16x32_bf16 v[64:67], v[170:173], v[218:221], v[64:67]
	v_mfma_f32_16x16x32_bf16 v[116:119], v[166:169], v[190:193], v[116:119]
	v_mfma_f32_16x16x32_bf16 v[112:115], v[174:177], v[190:193], v[112:115]
	v_mfma_f32_16x16x32_bf16 v[100:103], v[166:169], v[198:201], v[100:103]
	v_mfma_f32_16x16x32_bf16 v[96:99], v[174:177], v[198:201], v[96:99]
	v_mfma_f32_16x16x32_bf16 v[84:87], v[166:169], v[214:217], v[84:87]
	v_mfma_f32_16x16x32_bf16 v[80:83], v[174:177], v[214:217], v[80:83]
	v_mfma_f32_16x16x32_bf16 v[68:71], v[166:169], v[222:225], v[68:71]
	v_mfma_f32_16x16x32_bf16 v[64:67], v[174:177], v[222:225], v[64:67]
	s_barrier
	s_add_i32 s45, s45, s28
	v_lshl_add_u64 v[142:143], s[6:7], 0, v[182:183]
	s_mov_b32 m0, s45
	ds_read_b128 v[178:181], v149 offset:16384
	ds_read_b128 v[190:193], v149 offset:17408
	ds_read_b128 v[194:197], v149 offset:18432
	ds_read_b128 v[198:201], v149 offset:19456
	ds_read_b128 v[202:205], v149 offset:20480
	ds_read_b128 v[214:217], v149 offset:21504
	ds_read_b128 v[218:221], v149 offset:22528
	ds_read_b128 v[222:225], v149 offset:23552
	global_load_lds_dwordx4 v[142:143], off
	s_add_i32 m0, s45, 0x2000
	s_add_u32 s46, s6, 0x80000
	v_lshl_add_u64 v[188:189], s[6:7], 0, v[128:129]
	s_addc_u32 s47, s7, 0
	s_add_i32 s45, s48, s28
	global_load_lds_dwordx4 v[188:189], off
	v_lshl_add_u64 v[226:227], s[46:47], 0, v[182:183]
	s_mov_b32 m0, s45
	v_lshl_add_u64 v[228:229], s[24:25], 0, v[130:131]
	global_load_lds_dwordx4 v[226:227], off
	v_lshl_add_u64 v[226:227], s[46:47], 0, v[128:129]
	s_add_i32 m0, s45, 0x2000
	s_nop 0
	global_load_lds_dwordx4 v[226:227], off
	v_lshl_add_u64 v[226:227], s[24:25], 0, v[132:133]
	s_mov_b32 m0, s29
	s_nop 0
	global_load_lds_dwordx4 v[226:227], off
	s_mov_b32 m0, s30
	s_nop 0
	global_load_lds_dwordx4 v[228:229], off
	s_waitcnt vmcnt(8)
	s_waitcnt lgkmcnt(0)
	s_barrier
; #define PG8_STAGE(bufoff, gbase, voff) do { _Pragma("unroll") for (int _i = 0; _i < 2; ++_i) \
;         __builtin_amdgcn_global_load_lds((const unsigned*)((const char*)(gbase) + (voff)[_i]), (PG8_LAS unsigned*)(lds + (bufoff) + ldsw + _i * 8192), 16, 0, 0); } while (0)
; #define PG8_LDA(dst, b, h) do { _Pragma("unroll") for (int m = 0; m < 4; ++m) _Pragma("unroll") for (int k = 0; k < 2; ++k) dst[m][k] = *(const PG8_LAS bf16x8*)(lds + PG8_SA(b, h) + aoff + m * 2048 + k * 1024); } while (0)
; #define PG8_LDB(dst, b, h) do { _Pragma("unroll") for (int n = 0; n < 2; ++n) _Pragma("unroll") for (int k = 0; k < 2; ++k) dst[n][k] = *(const PG8_LAS bf16x8*)(lds + PG8_SB(b, h) + boff + n * 2048 + k * 1024); } while (0)
; #define PG8_MMA(ai, bj, At, Bt) do { __builtin_amdgcn_s_setprio(1); _Pragma("unroll") for (int m = 0; m < 4; ++m) _Pragma("unroll") for (int n = 0; n < 2; ++n) _Pragma("unroll") for (int k = 0; k < 2; ++k) \
;         acc[ai][bj][m][n] = __builtin_amdgcn_mfma_f32_16x16x32_bf16(Bt[n][k], At[m][k], acc[ai][bj][m][n], 0, 0, 0); __builtin_amdgcn_s_setprio(0); } while (0)
; #define PG8_WAIT_V(n) asm volatile("s_waitcnt vmcnt(" #n ")" ::: "memory")
; #define PG8_WAIT_L(n) asm volatile("s_waitcnt lgkmcnt(" #n ")" ::: "memory")
; #define PG8_BAR __builtin_amdgcn_s_barrier()
; #define PG8_SCHED __builtin_amdgcn_sched_barrier(0)
; template <class Epi, class Sched, bool ALIGN_EPI = false, bool SP2 = false>
; __device__ __forceinline__ void gemm_phase(PG8_LAS unsigned char* lds, const Gemm g, const Sched& S, const Epi& E, const int wid_in) {
;     ...
;             PG8_WAIT_V(8); PG8_WAIT_L(0); PG8_BAR; PG8_MMA(1, 0, At, B0); PG8_MMA(1, 1, At, B1); PG8_BAR; PG8_SCHED;
;             PG8_LDB(B0, 1, 0); PG8_LDB(B1, 1, 1); PG8_SCHED; PG8_LDA(At, 1, 0); PG8_STAGE(PG8_SA(0, 1), a2 + hstep, voffA);
;             PG8_WAIT_V(8); PG8_WAIT_L(0); PG8_BAR; PG8_MMA(0, 0, At, B0); PG8_MMA(0, 1, At, B1); PG8_BAR; PG8_SCHED;
	s_waitcnt lgkmcnt(0)
	v_mfma_f32_16x16x32_bf16 v[60:63], v[138:141], v[178:181], v[60:63]
	v_mfma_f32_16x16x32_bf16 v[56:59], v[154:157], v[178:181], v[56:59]
	v_mfma_f32_16x16x32_bf16 v[44:47], v[138:141], v[194:197], v[44:47]
	v_mfma_f32_16x16x32_bf16 v[40:43], v[154:157], v[194:197], v[40:43]
	v_mfma_f32_16x16x32_bf16 v[28:31], v[138:141], v[202:205], v[28:31]
	v_mfma_f32_16x16x32_bf16 v[24:27], v[154:157], v[202:205], v[24:27]
	v_mfma_f32_16x16x32_bf16 v[12:15], v[138:141], v[218:221], v[12:15]
	v_mfma_f32_16x16x32_bf16 v[8:11], v[154:157], v[218:221], v[8:11]
	v_mfma_f32_16x16x32_bf16 v[60:63], v[150:153], v[190:193], v[60:63]
	v_mfma_f32_16x16x32_bf16 v[56:59], v[158:161], v[190:193], v[56:59]
	v_mfma_f32_16x16x32_bf16 v[44:47], v[150:153], v[198:201], v[44:47]
	v_mfma_f32_16x16x32_bf16 v[40:43], v[158:161], v[198:201], v[40:43]
	v_mfma_f32_16x16x32_bf16 v[28:31], v[150:153], v[214:217], v[28:31]
	v_mfma_f32_16x16x32_bf16 v[24:27], v[158:161], v[214:217], v[24:27]
	v_mfma_f32_16x16x32_bf16 v[12:15], v[150:153], v[222:225], v[12:15]
	v_mfma_f32_16x16x32_bf16 v[8:11], v[158:161], v[222:225], v[8:11]
	v_mfma_f32_16x16x32_bf16 v[52:55], v[162:165], v[178:181], v[52:55]
	v_mfma_f32_16x16x32_bf16 v[48:51], v[170:173], v[178:181], v[48:51]
	v_mfma_f32_16x16x32_bf16 v[36:39], v[162:165], v[194:197], v[36:39]
	v_mfma_f32_16x16x32_bf16 v[32:35], v[170:173], v[194:197], v[32:35]
	v_mfma_f32_16x16x32_bf16 v[20:23], v[162:165], v[202:205], v[20:23]
	v_mfma_f32_16x16x32_bf16 v[16:19], v[170:173], v[202:205], v[16:19]
	v_mfma_f32_16x16x32_bf16 v[4:7], v[162:165], v[218:221], v[4:7]
	v_mfma_f32_16x16x32_bf16 v[0:3], v[170:173], v[218:221], v[0:3]
	v_mfma_f32_16x16x32_bf16 v[52:55], v[166:169], v[190:193], v[52:55]
	v_mfma_f32_16x16x32_bf16 v[48:51], v[174:177], v[190:193], v[48:51]
	v_mfma_f32_16x16x32_bf16 v[36:39], v[166:169], v[198:201], v[36:39]
	v_mfma_f32_16x16x32_bf16 v[32:35], v[174:177], v[198:201], v[32:35]
	v_mfma_f32_16x16x32_bf16 v[20:23], v[166:169], v[214:217], v[20:23]
	v_mfma_f32_16x16x32_bf16 v[16:19], v[174:177], v[214:217], v[16:19]
	v_mfma_f32_16x16x32_bf16 v[4:7], v[166:169], v[222:225], v[4:7]
	v_mfma_f32_16x16x32_bf16 v[0:3], v[174:177], v[222:225], v[0:3]
	s_barrier
	s_add_i32 s45, 0, 0x18000
	v_add_u32_e32 v144, s45, v147
	s_add_i32 s46, 0, 0x1c000
	ds_read_b128 v[138:141], v144
	ds_read_b128 v[150:153], v144 offset:1024
	ds_read_b128 v[154:157], v144 offset:2048
	ds_read_b128 v[158:161], v144 offset:3072
	v_add_u32_e32 v144, s46, v147
	ds_read_b128 v[162:165], v144
	ds_read_b128 v[166:169], v144 offset:1024
	ds_read_b128 v[170:173], v144 offset:2048
	ds_read_b128 v[174:177], v144 offset:3072
	s_add_u32 s24, s24, 0x80000
	s_addc_u32 s25, s25, 0
	s_mov_b32 m0, s31
	v_lshl_add_u64 v[230:231], s[24:25], 0, v[132:133]
	ds_read_b128 v[178:181], v149 offset:32768
	ds_read_b128 v[190:193], v149 offset:33792
	ds_read_b128 v[194:197], v149 offset:34816
	ds_read_b128 v[198:201], v149 offset:35840
	ds_read_b128 v[202:205], v149 offset:36864
	ds_read_b128 v[214:217], v149 offset:37888
	ds_read_b128 v[218:221], v149 offset:38912
	ds_read_b128 v[222:225], v149 offset:39936
	global_load_lds_dwordx4 v[230:231], off
	v_lshl_add_u64 v[230:231], s[24:25], 0, v[130:131]
	s_mov_b32 m0, s34
	s_nop 0
	global_load_lds_dwordx4 v[230:231], off
	s_waitcnt vmcnt(8)
	s_waitcnt lgkmcnt(0)
	s_barrier
	s_waitcnt lgkmcnt(0)
	v_mfma_f32_16x16x32_bf16 v[124:127], v[138:141], v[178:181], v[124:127]
	v_mfma_f32_16x16x32_bf16 v[120:123], v[154:157], v[178:181], v[120:123]
	v_mfma_f32_16x16x32_bf16 v[108:111], v[138:141], v[194:197], v[108:111]
	v_mfma_f32_16x16x32_bf16 v[104:107], v[154:157], v[194:197], v[104:107]
	v_mfma_f32_16x16x32_bf16 v[92:95], v[138:141], v[202:205], v[92:95]
	v_mfma_f32_16x16x32_bf16 v[88:91], v[154:157], v[202:205], v[88:91]
	v_mfma_f32_16x16x32_bf16 v[76:79], v[138:141], v[218:221], v[76:79]
	v_mfma_f32_16x16x32_bf16 v[72:75], v[154:157], v[218:221], v[72:75]
	v_mfma_f32_16x16x32_bf16 v[124:127], v[150:153], v[190:193], v[124:127]
	v_mfma_f32_16x16x32_bf16 v[120:123], v[158:161], v[190:193], v[120:123]
	v_mfma_f32_16x16x32_bf16 v[108:111], v[150:153], v[198:201], v[108:111]
	v_mfma_f32_16x16x32_bf16 v[104:107], v[158:161], v[198:201], v[104:107]
	v_mfma_f32_16x16x32_bf16 v[92:95], v[150:153], v[214:217], v[92:95]
	v_mfma_f32_16x16x32_bf16 v[88:91], v[158:161], v[214:217], v[88:91]
	v_mfma_f32_16x16x32_bf16 v[76:79], v[150:153], v[222:225], v[76:79]
	v_mfma_f32_16x16x32_bf16 v[72:75], v[158:161], v[222:225], v[72:75]
	v_mfma_f32_16x16x32_bf16 v[116:119], v[162:165], v[178:181], v[116:119]
	v_mfma_f32_16x16x32_bf16 v[112:115], v[170:173], v[178:181], v[112:115]
	v_mfma_f32_16x16x32_bf16 v[100:103], v[162:165], v[194:197], v[100:103]
	v_mfma_f32_16x16x32_bf16 v[96:99], v[170:173], v[194:197], v[96:99]
	v_mfma_f32_16x16x32_bf16 v[84:87], v[162:165], v[202:205], v[84:87]
	v_mfma_f32_16x16x32_bf16 v[80:83], v[170:173], v[202:205], v[80:83]
	v_mfma_f32_16x16x32_bf16 v[68:71], v[162:165], v[218:221], v[68:71]
	v_mfma_f32_16x16x32_bf16 v[64:67], v[170:173], v[218:221], v[64:67]
	v_mfma_f32_16x16x32_bf16 v[116:119], v[166:169], v[190:193], v[116:119]
	v_mfma_f32_16x16x32_bf16 v[112:115], v[174:177], v[190:193], v[112:115]
	v_mfma_f32_16x16x32_bf16 v[100:103], v[166:169], v[198:201], v[100:103]
	v_mfma_f32_16x16x32_bf16 v[96:99], v[174:177], v[198:201], v[96:99]
	v_mfma_f32_16x16x32_bf16 v[84:87], v[166:169], v[214:217], v[84:87]
	v_mfma_f32_16x16x32_bf16 v[80:83], v[174:177], v[214:217], v[80:83]
	v_mfma_f32_16x16x32_bf16 v[68:71], v[166:169], v[222:225], v[68:71]
	v_mfma_f32_16x16x32_bf16 v[64:67], v[174:177], v[222:225], v[64:67]
	s_barrier
; #define PG8_STAGE(bufoff, gbase, voff) do { _Pragma("unroll") for (int _i = 0; _i < 2; ++_i) \
;         __builtin_amdgcn_global_load_lds((const unsigned*)((const char*)(gbase) + (voff)[_i]), (PG8_LAS unsigned*)(lds + (bufoff) + ldsw + _i * 8192), 16, 0, 0); } while (0)
; #define PG8_LDA(dst, b, h) do { _Pragma("unroll") for (int m = 0; m < 4; ++m) _Pragma("unroll") for (int k = 0; k < 2; ++k) dst[m][k] = *(const PG8_LAS bf16x8*)(lds + PG8_SA(b, h) + aoff + m * 2048 + k * 1024); } while (0)
; #define PG8_MMA(ai, bj, At, Bt) do { __builtin_amdgcn_s_setprio(1); _Pragma("unroll") for (int m = 0; m < 4; ++m) _Pragma("unroll") for (int n = 0; n < 2; ++n) _Pragma("unroll") for (int k = 0; k < 2; ++k) \
;         acc[ai][bj][m][n] = __builtin_amdgcn_mfma_f32_16x16x32_bf16(Bt[n][k], At[m][k], acc[ai][bj][m][n], 0, 0, 0); __builtin_amdgcn_s_setprio(0); } while (0)
; #define PG8_WAIT_V(n) asm volatile("s_waitcnt vmcnt(" #n ")" ::: "memory")
; #define PG8_WAIT_L(n) asm volatile("s_waitcnt lgkmcnt(" #n ")" ::: "memory")
; #define PG8_BAR __builtin_amdgcn_s_barrier()
; #define PG8_SCHED __builtin_amdgcn_sched_barrier(0)
; template <class Epi, class Sched, bool ALIGN_EPI = false, bool SP2 = false>
; __device__ __forceinline__ void gemm_phase(PG8_LAS unsigned char* lds, const Gemm g, const Sched& S, const Epi& E, const int wid_in) {
;     ...
;         for (int t = 0; t < nt; t += 2) {
;             const bool last = (t == nt - 2);
;     ...
;             PG8_LDA(At, 1, 1); PG8_STAGE(PG8_SB(1, 0), b3, voffB); PG8_STAGE(PG8_SB(1, 1), b3 + hstep, voffB); PG8_STAGE(PG8_SA(1, 0), a3, voffA);
;             PG8_WAIT_V(8); PG8_WAIT_L(0); PG8_BAR; PG8_MMA(1, 0, At, B0); PG8_MMA(1, 1, At, B1); PG8_BAR; PG8_SCHED;
	s_add_i32 s24, s45, s28
	v_lshl_add_u64 v[142:143], v[142:143], 0, s[74:75]
	s_mov_b32 m0, s24
	ds_read_b128 v[178:181], v149 offset:49152
	ds_read_b128 v[190:193], v149 offset:50176
	ds_read_b128 v[194:197], v149 offset:51200
	ds_read_b128 v[198:201], v149 offset:52224
	ds_read_b128 v[202:205], v149 offset:53248
	ds_read_b128 v[214:217], v149 offset:54272
	ds_read_b128 v[218:221], v149 offset:55296
	ds_read_b128 v[222:225], v149 offset:56320
	global_load_lds_dwordx4 v[142:143], off
	s_add_i32 m0, s24, 0x2000
	s_add_u32 s6, s6, 0x80080
	v_lshl_add_u64 v[142:143], v[188:189], 0, s[74:75]
	s_addc_u32 s7, s7, 0
	s_add_i32 s24, s46, s28
	global_load_lds_dwordx4 v[142:143], off
	v_lshl_add_u64 v[142:143], s[6:7], 0, v[182:183]
	s_mov_b32 m0, s24
	s_nop 0
	global_load_lds_dwordx4 v[142:143], off
	v_lshl_add_u64 v[142:143], s[6:7], 0, v[128:129]
	s_add_i32 m0, s24, 0x2000
	s_nop 0
	global_load_lds_dwordx4 v[142:143], off
	v_lshl_add_u64 v[142:143], v[226:227], 0, s[74:75]
	s_mov_b32 m0, s35
	s_nop 0
	global_load_lds_dwordx4 v[142:143], off
	v_lshl_add_u64 v[142:143], v[228:229], 0, s[74:75]
	s_mov_b32 m0, s36
	s_nop 0
	global_load_lds_dwordx4 v[142:143], off
	s_waitcnt vmcnt(8)
	s_waitcnt lgkmcnt(0)
	s_barrier
	s_waitcnt lgkmcnt(0)
	v_mfma_f32_16x16x32_bf16 v[60:63], v[138:141], v[178:181], v[60:63]
	v_mfma_f32_16x16x32_bf16 v[56:59], v[154:157], v[178:181], v[56:59]
	v_mfma_f32_16x16x32_bf16 v[44:47], v[138:141], v[194:197], v[44:47]
	v_mfma_f32_16x16x32_bf16 v[40:43], v[154:157], v[194:197], v[40:43]
	v_mfma_f32_16x16x32_bf16 v[28:31], v[138:141], v[202:205], v[28:31]
	v_mfma_f32_16x16x32_bf16 v[24:27], v[154:157], v[202:205], v[24:27]
	v_mfma_f32_16x16x32_bf16 v[12:15], v[138:141], v[218:221], v[12:15]
	v_mfma_f32_16x16x32_bf16 v[8:11], v[154:157], v[218:221], v[8:11]
	v_mfma_f32_16x16x32_bf16 v[60:63], v[150:153], v[190:193], v[60:63]
	v_mfma_f32_16x16x32_bf16 v[56:59], v[158:161], v[190:193], v[56:59]
	v_mfma_f32_16x16x32_bf16 v[44:47], v[150:153], v[198:201], v[44:47]
	v_mfma_f32_16x16x32_bf16 v[40:43], v[158:161], v[198:201], v[40:43]
	v_mfma_f32_16x16x32_bf16 v[28:31], v[150:153], v[214:217], v[28:31]
	v_mfma_f32_16x16x32_bf16 v[24:27], v[158:161], v[214:217], v[24:27]
	v_mfma_f32_16x16x32_bf16 v[12:15], v[150:153], v[222:225], v[12:15]
	v_mfma_f32_16x16x32_bf16 v[8:11], v[158:161], v[222:225], v[8:11]
	v_mfma_f32_16x16x32_bf16 v[52:55], v[162:165], v[178:181], v[52:55]
	v_mfma_f32_16x16x32_bf16 v[48:51], v[170:173], v[178:181], v[48:51]
	v_mfma_f32_16x16x32_bf16 v[36:39], v[162:165], v[194:197], v[36:39]
	v_mfma_f32_16x16x32_bf16 v[32:35], v[170:173], v[194:197], v[32:35]
	v_mfma_f32_16x16x32_bf16 v[20:23], v[162:165], v[202:205], v[20:23]
	v_mfma_f32_16x16x32_bf16 v[16:19], v[170:173], v[202:205], v[16:19]
	v_mfma_f32_16x16x32_bf16 v[4:7], v[162:165], v[218:221], v[4:7]
	v_mfma_f32_16x16x32_bf16 v[0:3], v[170:173], v[218:221], v[0:3]
	v_mfma_f32_16x16x32_bf16 v[52:55], v[166:169], v[190:193], v[52:55]
	v_mfma_f32_16x16x32_bf16 v[48:51], v[174:177], v[190:193], v[48:51]
	v_mfma_f32_16x16x32_bf16 v[36:39], v[166:169], v[198:201], v[36:39]
	v_mfma_f32_16x16x32_bf16 v[32:35], v[174:177], v[198:201], v[32:35]
	v_mfma_f32_16x16x32_bf16 v[20:23], v[166:169], v[214:217], v[20:23]
	v_mfma_f32_16x16x32_bf16 v[16:19], v[174:177], v[214:217], v[16:19]
	v_mfma_f32_16x16x32_bf16 v[4:7], v[166:169], v[222:225], v[4:7]
	v_mfma_f32_16x16x32_bf16 v[0:3], v[174:177], v[222:225], v[0:3]
	s_barrier
	s_add_i32 s44, s44, 2
	s_add_u32 s4, s4, 0x100
	s_addc_u32 s5, s5, 0
	s_add_u32 s42, s42, 0x100
	s_addc_u32 s43, s43, 0
	s_cmp_gt_u32 s44, 29
	s_cbranch_scc0 .LBB0_133
	s_and_b64 vcc, exec, s[14:15]
	s_cbranch_vccz .LBB0_136
	s_barrier

; #define PG8_STAGE(bufoff, gbase, voff) do { _Pragma("unroll") for (int _i = 0; _i < 2; ++_i) \
;         __builtin_amdgcn_global_load_lds((const unsigned*)((const char*)(gbase) + (voff)[_i]), (PG8_LAS unsigned*)(lds + (bufoff) + ldsw + _i * 8192), 16, 0, 0); } while (0)
; #define PG8_LDA(dst, b, h) do { _Pragma("unroll") for (int m = 0; m < 4; ++m) _Pragma("unroll") for (int k = 0; k < 2; ++k) dst[m][k] = *(const PG8_LAS bf16x8*)(lds + PG8_SA(b, h) + aoff + m * 2048 + k * 1024); } while (0)
; #define PG8_LDB(dst, b, h) do { _Pragma("unroll") for (int n = 0; n < 2; ++n) _Pragma("unroll") for (int k = 0; k < 2; ++k) dst[n][k] = *(const PG8_LAS bf16x8*)(lds + PG8_SB(b, h) + boff + n * 2048 + k * 1024); } while (0)
; #define PG8_MMA(ai, bj, At, Bt) do { __builtin_amdgcn_s_setprio(1); _Pragma("unroll") for (int m = 0; m < 4; ++m) _Pragma("unroll") for (int n = 0; n < 2; ++n) _Pragma("unroll") for (int k = 0; k < 2; ++k) \
;         acc[ai][bj][m][n] = __builtin_amdgcn_mfma_f32_16x16x32_bf16(Bt[n][k], At[m][k], acc[ai][bj][m][n], 0, 0, 0); __builtin_amdgcn_s_setprio(0); } while (0)
; #define PG8_WAIT_V(n) asm volatile("s_waitcnt vmcnt(" #n ")" ::: "memory")
; #define PG8_WAIT_L(n) asm volatile("s_waitcnt lgkmcnt(" #n ")" ::: "memory")
; #define PG8_BAR __builtin_amdgcn_s_barrier()
; #define PG8_SCHED __builtin_amdgcn_sched_barrier(0)
; template <class Epi, class Sched, bool ALIGN_EPI = false, bool SP2 = false>
; __device__ __forceinline__ void gemm_phase(PG8_LAS unsigned char* lds, const Gemm g, const Sched& S, const Epi& E, const int wid_in) {
;     ...
;             PG8_LDB(B0, 0, 0); PG8_LDB(B1, 0, 1); PG8_SCHED; PG8_LDA(At, 0, 0); PG8_STAGE(PG8_SA(1, 1), a1 + hstep, voffA);
;             PG8_WAIT_V(8); PG8_WAIT_L(0); PG8_BAR; PG8_MMA(0, 0, At, B0); PG8_MMA(0, 1, At, B1); PG8_BAR; PG8_SCHED;
;             PG8_LDA(At, 0, 1); PG8_STAGE(PG8_SB(0, 0), b2, voffB); PG8_STAGE(PG8_SB(0, 1), b2 + hstep, voffB); PG8_STAGE(PG8_SA(0, 0), a2, voffA);
;             PG8_WAIT_V(8); PG8_WAIT_L(0); PG8_BAR; PG8_MMA(1, 0, At, B0); PG8_MMA(1, 1, At, B1); PG8_BAR; PG8_SCHED;
.LBB0_167:
	s_add_u32 s6, s4, 0xfff80080
	s_addc_u32 s7, s5, -1
	s_add_i32 s45, 0, 0x10000
	s_cmp_eq_u32 s44, 28
	s_cselect_b32 s25, s19, s7
	s_cselect_b32 s24, s40, s6
	v_add_u32_e32 v138, s45, v147
	s_cselect_b32 s7, s17, s43
	s_cselect_b32 s6, s41, s42
	s_add_i32 s48, 0, 0x14000
	ds_read_b128 v[140:143], v138
	ds_read_b128 v[150:153], v138 offset:1024
	ds_read_b128 v[154:157], v138 offset:2048
	ds_read_b128 v[158:161], v138 offset:3072
	v_add_u32_e32 v138, s48, v147
	ds_read_b128 v[162:165], v138
	ds_read_b128 v[166:169], v138 offset:1024
	ds_read_b128 v[170:173], v138 offset:2048
	ds_read_b128 v[174:177], v138 offset:3072
	v_lshl_add_u64 v[144:145], s[4:5], 0, v[134:135]
	s_add_i32 m0, s29, 0xc000
	ds_read_b128 v[178:181], v149
	ds_read_b128 v[190:193], v149 offset:1024
	ds_read_b128 v[194:197], v149 offset:2048
	ds_read_b128 v[198:201], v149 offset:3072
	ds_read_b128 v[202:205], v149 offset:4096
	ds_read_b128 v[214:217], v149 offset:5120
	ds_read_b128 v[218:221], v149 offset:6144
	ds_read_b128 v[222:225], v149 offset:7168
	global_load_lds_dwordx4 v[144:145], off
	v_lshl_add_u64 v[144:145], s[4:5], 0, v[136:137]
	s_add_i32 m0, s29, 0xe000
	s_nop 0
	global_load_lds_dwordx4 v[144:145], off
	s_waitcnt vmcnt(8)
	s_waitcnt lgkmcnt(0)
	s_barrier
	s_waitcnt lgkmcnt(0)
	v_mfma_f32_16x16x32_bf16 v[124:127], v[140:143], v[178:181], v[124:127]
	v_mfma_f32_16x16x32_bf16 v[120:123], v[154:157], v[178:181], v[120:123]
	v_mfma_f32_16x16x32_bf16 v[108:111], v[140:143], v[194:197], v[108:111]
	v_mfma_f32_16x16x32_bf16 v[104:107], v[154:157], v[194:197], v[104:107]
	v_mfma_f32_16x16x32_bf16 v[92:95], v[140:143], v[202:205], v[92:95]
	v_mfma_f32_16x16x32_bf16 v[88:91], v[154:157], v[202:205], v[88:91]
	v_mfma_f32_16x16x32_bf16 v[76:79], v[140:143], v[218:221], v[76:79]
	v_mfma_f32_16x16x32_bf16 v[72:75], v[154:157], v[218:221], v[72:75]
	v_mfma_f32_16x16x32_bf16 v[124:127], v[150:153], v[190:193], v[124:127]
	v_mfma_f32_16x16x32_bf16 v[120:123], v[158:161], v[190:193], v[120:123]
	v_mfma_f32_16x16x32_bf16 v[108:111], v[150:153], v[198:201], v[108:111]
	v_mfma_f32_16x16x32_bf16 v[104:107], v[158:161], v[198:201], v[104:107]
	v_mfma_f32_16x16x32_bf16 v[92:95], v[150:153], v[214:217], v[92:95]
	v_mfma_f32_16x16x32_bf16 v[88:91], v[158:161], v[214:217], v[88:91]
	v_mfma_f32_16x16x32_bf16 v[76:79], v[150:153], v[222:225], v[76:79]
	v_mfma_f32_16x16x32_bf16 v[72:75], v[158:161], v[222:225], v[72:75]
	v_mfma_f32_16x16x32_bf16 v[116:119], v[162:165], v[178:181], v[116:119]
	v_mfma_f32_16x16x32_bf16 v[112:115], v[170:173], v[178:181], v[112:115]
	v_mfma_f32_16x16x32_bf16 v[100:103], v[162:165], v[194:197], v[100:103]
	v_mfma_f32_16x16x32_bf16 v[96:99], v[170:173], v[194:197], v[96:99]
	v_mfma_f32_16x16x32_bf16 v[84:87], v[162:165], v[202:205], v[84:87]
	v_mfma_f32_16x16x32_bf16 v[80:83], v[170:173], v[202:205], v[80:83]
	v_mfma_f32_16x16x32_bf16 v[68:71], v[162:165], v[218:221], v[68:71]
	v_mfma_f32_16x16x32_bf16 v[64:67], v[170:173], v[218:221], v[64:67]
	v_mfma_f32_16x16x32_bf16 v[116:119], v[166:169], v[190:193], v[116:119]
	v_mfma_f32_16x16x32_bf16 v[112:115], v[174:177], v[190:193], v[112:115]
	v_mfma_f32_16x16x32_bf16 v[100:103], v[166:169], v[198:201], v[100:103]
	v_mfma_f32_16x16x32_bf16 v[96:99], v[174:177], v[198:201], v[96:99]
	v_mfma_f32_16x16x32_bf16 v[84:87], v[166:169], v[214:217], v[84:87]
	v_mfma_f32_16x16x32_bf16 v[80:83], v[174:177], v[214:217], v[80:83]
	v_mfma_f32_16x16x32_bf16 v[68:71], v[166:169], v[222:225], v[68:71]
	v_mfma_f32_16x16x32_bf16 v[64:67], v[174:177], v[222:225], v[64:67]
	s_barrier
	s_add_i32 s45, s45, s28
	v_lshl_add_u64 v[144:145], s[6:7], 0, v[182:183]
	s_mov_b32 m0, s45
	ds_read_b128 v[178:181], v149 offset:16384
	ds_read_b128 v[190:193], v149 offset:17408
	ds_read_b128 v[194:197], v149 offset:18432
	ds_read_b128 v[198:201], v149 offset:19456
	ds_read_b128 v[202:205], v149 offset:20480
	ds_read_b128 v[214:217], v149 offset:21504
	ds_read_b128 v[218:221], v149 offset:22528
	ds_read_b128 v[222:225], v149 offset:23552
	global_load_lds_dwordx4 v[144:145], off
	s_add_i32 m0, s45, 0x2000
	s_add_u32 s46, s6, 0x80000
	v_lshl_add_u64 v[188:189], s[6:7], 0, v[128:129]
	s_addc_u32 s47, s7, 0
	s_add_i32 s45, s48, s28
	global_load_lds_dwordx4 v[188:189], off
	v_lshl_add_u64 v[226:227], s[46:47], 0, v[182:183]
	s_mov_b32 m0, s45
	v_lshl_add_u64 v[228:229], s[24:25], 0, v[130:131]
	global_load_lds_dwordx4 v[226:227], off
	v_lshl_add_u64 v[226:227], s[46:47], 0, v[128:129]
	s_add_i32 m0, s45, 0x2000
	s_nop 0
	global_load_lds_dwordx4 v[226:227], off
	v_lshl_add_u64 v[226:227], s[24:25], 0, v[132:133]
	s_mov_b32 m0, s29
	s_nop 0
	global_load_lds_dwordx4 v[226:227], off
	s_mov_b32 m0, s30
	s_nop 0
	global_load_lds_dwordx4 v[228:229], off
	s_waitcnt vmcnt(8)
	s_waitcnt lgkmcnt(0)
	s_barrier
; #define PG8_STAGE(bufoff, gbase, voff) do { _Pragma("unroll") for (int _i = 0; _i < 2; ++_i) \
;         __builtin_amdgcn_global_load_lds((const unsigned*)((const char*)(gbase) + (voff)[_i]), (PG8_LAS unsigned*)(lds + (bufoff) + ldsw + _i * 8192), 16, 0, 0); } while (0)
; #define PG8_LDA(dst, b, h) do { _Pragma("unroll") for (int m = 0; m < 4; ++m) _Pragma("unroll") for (int k = 0; k < 2; ++k) dst[m][k] = *(const PG8_LAS bf16x8*)(lds + PG8_SA(b, h) + aoff + m * 2048 + k * 1024); } while (0)
; #define PG8_LDB(dst, b, h) do { _Pragma("unroll") for (int n = 0; n < 2; ++n) _Pragma("unroll") for (int k = 0; k < 2; ++k) dst[n][k] = *(const PG8_LAS bf16x8*)(lds + PG8_SB(b, h) + boff + n * 2048 + k * 1024); } while (0)
; #define PG8_MMA(ai, bj, At, Bt) do { __builtin_amdgcn_s_setprio(1); _Pragma("unroll") for (int m = 0; m < 4; ++m) _Pragma("unroll") for (int n = 0; n < 2; ++n) _Pragma("unroll") for (int k = 0; k < 2; ++k) \
;         acc[ai][bj][m][n] = __builtin_amdgcn_mfma_f32_16x16x32_bf16(Bt[n][k], At[m][k], acc[ai][bj][m][n], 0, 0, 0); __builtin_amdgcn_s_setprio(0); } while (0)
; #define PG8_WAIT_V(n) asm volatile("s_waitcnt vmcnt(" #n ")" ::: "memory")
; #define PG8_WAIT_L(n) asm volatile("s_waitcnt lgkmcnt(" #n ")" ::: "memory")
; #define PG8_BAR __builtin_amdgcn_s_barrier()
; #define PG8_SCHED __builtin_amdgcn_sched_barrier(0)
; template <class Epi, class Sched, bool ALIGN_EPI = false, bool SP2 = false>
; __device__ __forceinline__ void gemm_phase(PG8_LAS unsigned char* lds, const Gemm g, const Sched& S, const Epi& E, const int wid_in) {
;     ...
;             PG8_WAIT_V(8); PG8_WAIT_L(0); PG8_BAR; PG8_MMA(1, 0, At, B0); PG8_MMA(1, 1, At, B1); PG8_BAR; PG8_SCHED;
;             PG8_LDB(B0, 1, 0); PG8_LDB(B1, 1, 1); PG8_SCHED; PG8_LDA(At, 1, 0); PG8_STAGE(PG8_SA(0, 1), a2 + hstep, voffA);
;             PG8_WAIT_V(8); PG8_WAIT_L(0); PG8_BAR; PG8_MMA(0, 0, At, B0); PG8_MMA(0, 1, At, B1); PG8_BAR; PG8_SCHED;
	s_waitcnt lgkmcnt(0)
	v_mfma_f32_16x16x32_bf16 v[60:63], v[140:143], v[178:181], v[60:63]
	v_mfma_f32_16x16x32_bf16 v[56:59], v[154:157], v[178:181], v[56:59]
	v_mfma_f32_16x16x32_bf16 v[44:47], v[140:143], v[194:197], v[44:47]
	v_mfma_f32_16x16x32_bf16 v[40:43], v[154:157], v[194:197], v[40:43]
	v_mfma_f32_16x16x32_bf16 v[28:31], v[140:143], v[202:205], v[28:31]
	v_mfma_f32_16x16x32_bf16 v[24:27], v[154:157], v[202:205], v[24:27]
	v_mfma_f32_16x16x32_bf16 v[12:15], v[140:143], v[218:221], v[12:15]
	v_mfma_f32_16x16x32_bf16 v[8:11], v[154:157], v[218:221], v[8:11]
	v_mfma_f32_16x16x32_bf16 v[60:63], v[150:153], v[190:193], v[60:63]
	v_mfma_f32_16x16x32_bf16 v[56:59], v[158:161], v[190:193], v[56:59]
	v_mfma_f32_16x16x32_bf16 v[44:47], v[150:153], v[198:201], v[44:47]
	v_mfma_f32_16x16x32_bf16 v[40:43], v[158:161], v[198:201], v[40:43]
	v_mfma_f32_16x16x32_bf16 v[28:31], v[150:153], v[214:217], v[28:31]
	v_mfma_f32_16x16x32_bf16 v[24:27], v[158:161], v[214:217], v[24:27]
	v_mfma_f32_16x16x32_bf16 v[12:15], v[150:153], v[222:225], v[12:15]
	v_mfma_f32_16x16x32_bf16 v[8:11], v[158:161], v[222:225], v[8:11]
	v_mfma_f32_16x16x32_bf16 v[52:55], v[162:165], v[178:181], v[52:55]
	v_mfma_f32_16x16x32_bf16 v[48:51], v[170:173], v[178:181], v[48:51]
	v_mfma_f32_16x16x32_bf16 v[36:39], v[162:165], v[194:197], v[36:39]
	v_mfma_f32_16x16x32_bf16 v[32:35], v[170:173], v[194:197], v[32:35]
	v_mfma_f32_16x16x32_bf16 v[20:23], v[162:165], v[202:205], v[20:23]
	v_mfma_f32_16x16x32_bf16 v[16:19], v[170:173], v[202:205], v[16:19]
	v_mfma_f32_16x16x32_bf16 v[4:7], v[162:165], v[218:221], v[4:7]
	v_mfma_f32_16x16x32_bf16 v[0:3], v[170:173], v[218:221], v[0:3]
	v_mfma_f32_16x16x32_bf16 v[52:55], v[166:169], v[190:193], v[52:55]
	v_mfma_f32_16x16x32_bf16 v[48:51], v[174:177], v[190:193], v[48:51]
	v_mfma_f32_16x16x32_bf16 v[36:39], v[166:169], v[198:201], v[36:39]
	v_mfma_f32_16x16x32_bf16 v[32:35], v[174:177], v[198:201], v[32:35]
	v_mfma_f32_16x16x32_bf16 v[20:23], v[166:169], v[214:217], v[20:23]
	v_mfma_f32_16x16x32_bf16 v[16:19], v[174:177], v[214:217], v[16:19]
	v_mfma_f32_16x16x32_bf16 v[4:7], v[166:169], v[222:225], v[4:7]
	v_mfma_f32_16x16x32_bf16 v[0:3], v[174:177], v[222:225], v[0:3]
	s_barrier
	s_add_i32 s45, 0, 0x18000
	v_add_u32_e32 v138, s45, v147
	s_add_i32 s46, 0, 0x1c000
	ds_read_b128 v[140:143], v138
	ds_read_b128 v[150:153], v138 offset:1024
	ds_read_b128 v[154:157], v138 offset:2048
	ds_read_b128 v[158:161], v138 offset:3072
	v_add_u32_e32 v138, s46, v147
	ds_read_b128 v[162:165], v138
	ds_read_b128 v[166:169], v138 offset:1024
	ds_read_b128 v[170:173], v138 offset:2048
	ds_read_b128 v[174:177], v138 offset:3072
	s_add_u32 s24, s24, 0x80000
	s_addc_u32 s25, s25, 0
	s_mov_b32 m0, s31
	v_lshl_add_u64 v[230:231], s[24:25], 0, v[132:133]
	ds_read_b128 v[178:181], v149 offset:32768
	ds_read_b128 v[190:193], v149 offset:33792
	ds_read_b128 v[194:197], v149 offset:34816
	ds_read_b128 v[198:201], v149 offset:35840
	ds_read_b128 v[202:205], v149 offset:36864
	ds_read_b128 v[214:217], v149 offset:37888
	ds_read_b128 v[218:221], v149 offset:38912
	ds_read_b128 v[222:225], v149 offset:39936
	global_load_lds_dwordx4 v[230:231], off
	v_lshl_add_u64 v[230:231], s[24:25], 0, v[130:131]
	s_mov_b32 m0, s34
	s_nop 0
	global_load_lds_dwordx4 v[230:231], off
	s_waitcnt vmcnt(8)
	s_waitcnt lgkmcnt(0)
	s_barrier
	s_waitcnt lgkmcnt(0)
	v_mfma_f32_16x16x32_bf16 v[124:127], v[140:143], v[178:181], v[124:127]
	v_mfma_f32_16x16x32_bf16 v[120:123], v[154:157], v[178:181], v[120:123]
	v_mfma_f32_16x16x32_bf16 v[108:111], v[140:143], v[194:197], v[108:111]
	v_mfma_f32_16x16x32_bf16 v[104:107], v[154:157], v[194:197], v[104:107]
	v_mfma_f32_16x16x32_bf16 v[92:95], v[140:143], v[202:205], v[92:95]
	v_mfma_f32_16x16x32_bf16 v[88:91], v[154:157], v[202:205], v[88:91]
	v_mfma_f32_16x16x32_bf16 v[76:79], v[140:143], v[218:221], v[76:79]
	v_mfma_f32_16x16x32_bf16 v[72:75], v[154:157], v[218:221], v[72:75]
	v_mfma_f32_16x16x32_bf16 v[124:127], v[150:153], v[190:193], v[124:127]
	v_mfma_f32_16x16x32_bf16 v[120:123], v[158:161], v[190:193], v[120:123]
	v_mfma_f32_16x16x32_bf16 v[108:111], v[150:153], v[198:201], v[108:111]
	v_mfma_f32_16x16x32_bf16 v[104:107], v[158:161], v[198:201], v[104:107]
	v_mfma_f32_16x16x32_bf16 v[92:95], v[150:153], v[214:217], v[92:95]
	v_mfma_f32_16x16x32_bf16 v[88:91], v[158:161], v[214:217], v[88:91]
	v_mfma_f32_16x16x32_bf16 v[76:79], v[150:153], v[222:225], v[76:79]
	v_mfma_f32_16x16x32_bf16 v[72:75], v[158:161], v[222:225], v[72:75]
	v_mfma_f32_16x16x32_bf16 v[116:119], v[162:165], v[178:181], v[116:119]
	v_mfma_f32_16x16x32_bf16 v[112:115], v[170:173], v[178:181], v[112:115]
	v_mfma_f32_16x16x32_bf16 v[100:103], v[162:165], v[194:197], v[100:103]
	v_mfma_f32_16x16x32_bf16 v[96:99], v[170:173], v[194:197], v[96:99]
	v_mfma_f32_16x16x32_bf16 v[84:87], v[162:165], v[202:205], v[84:87]
	v_mfma_f32_16x16x32_bf16 v[80:83], v[170:173], v[202:205], v[80:83]
	v_mfma_f32_16x16x32_bf16 v[68:71], v[162:165], v[218:221], v[68:71]
	v_mfma_f32_16x16x32_bf16 v[64:67], v[170:173], v[218:221], v[64:67]
	v_mfma_f32_16x16x32_bf16 v[116:119], v[166:169], v[190:193], v[116:119]
	v_mfma_f32_16x16x32_bf16 v[112:115], v[174:177], v[190:193], v[112:115]
	v_mfma_f32_16x16x32_bf16 v[100:103], v[166:169], v[198:201], v[100:103]
	v_mfma_f32_16x16x32_bf16 v[96:99], v[174:177], v[198:201], v[96:99]
	v_mfma_f32_16x16x32_bf16 v[84:87], v[166:169], v[214:217], v[84:87]
	v_mfma_f32_16x16x32_bf16 v[80:83], v[174:177], v[214:217], v[80:83]
	v_mfma_f32_16x16x32_bf16 v[68:71], v[166:169], v[222:225], v[68:71]
	v_mfma_f32_16x16x32_bf16 v[64:67], v[174:177], v[222:225], v[64:67]
	s_barrier
; #define PG8_STAGE(bufoff, gbase, voff) do { _Pragma("unroll") for (int _i = 0; _i < 2; ++_i) \
;         __builtin_amdgcn_global_load_lds((const unsigned*)((const char*)(gbase) + (voff)[_i]), (PG8_LAS unsigned*)(lds + (bufoff) + ldsw + _i * 8192), 16, 0, 0); } while (0)
; #define PG8_LDA(dst, b, h) do { _Pragma("unroll") for (int m = 0; m < 4; ++m) _Pragma("unroll") for (int k = 0; k < 2; ++k) dst[m][k] = *(const PG8_LAS bf16x8*)(lds + PG8_SA(b, h) + aoff + m * 2048 + k * 1024); } while (0)
; #define PG8_MMA(ai, bj, At, Bt) do { __builtin_amdgcn_s_setprio(1); _Pragma("unroll") for (int m = 0; m < 4; ++m) _Pragma("unroll") for (int n = 0; n < 2; ++n) _Pragma("unroll") for (int k = 0; k < 2; ++k) \
;         acc[ai][bj][m][n] = __builtin_amdgcn_mfma_f32_16x16x32_bf16(Bt[n][k], At[m][k], acc[ai][bj][m][n], 0, 0, 0); __builtin_amdgcn_s_setprio(0); } while (0)
; #define PG8_WAIT_V(n) asm volatile("s_waitcnt vmcnt(" #n ")" ::: "memory")
; #define PG8_WAIT_L(n) asm volatile("s_waitcnt lgkmcnt(" #n ")" ::: "memory")
; #define PG8_BAR __builtin_amdgcn_s_barrier()
; #define PG8_SCHED __builtin_amdgcn_sched_barrier(0)
; template <class Epi, class Sched, bool ALIGN_EPI = false, bool SP2 = false>
; __device__ __forceinline__ void gemm_phase(PG8_LAS unsigned char* lds, const Gemm g, const Sched& S, const Epi& E, const int wid_in) {
;     ...
;         for (int t = 0; t < nt; t += 2) {
;             const bool last = (t == nt - 2);
;     ...
;             PG8_LDA(At, 1, 1); PG8_STAGE(PG8_SB(1, 0), b3, voffB); PG8_STAGE(PG8_SB(1, 1), b3 + hstep, voffB); PG8_STAGE(PG8_SA(1, 0), a3, voffA);
;             PG8_WAIT_V(8); PG8_WAIT_L(0); PG8_BAR; PG8_MMA(1, 0, At, B0); PG8_MMA(1, 1, At, B1); PG8_BAR; PG8_SCHED;
	s_add_i32 s24, s45, s28
	v_lshl_add_u64 v[144:145], v[144:145], 0, s[74:75]
	s_mov_b32 m0, s24
	ds_read_b128 v[178:181], v149 offset:49152
	ds_read_b128 v[190:193], v149 offset:50176
	ds_read_b128 v[194:197], v149 offset:51200
	ds_read_b128 v[198:201], v149 offset:52224
	ds_read_b128 v[202:205], v149 offset:53248
	ds_read_b128 v[214:217], v149 offset:54272
	ds_read_b128 v[218:221], v149 offset:55296
	ds_read_b128 v[222:225], v149 offset:56320
	global_load_lds_dwordx4 v[144:145], off
	s_add_i32 m0, s24, 0x2000
	s_add_u32 s6, s6, 0x80080
	v_lshl_add_u64 v[144:145], v[188:189], 0, s[74:75]
	s_addc_u32 s7, s7, 0
	s_add_i32 s24, s46, s28
	global_load_lds_dwordx4 v[144:145], off
	v_lshl_add_u64 v[144:145], s[6:7], 0, v[182:183]
	s_mov_b32 m0, s24
	s_nop 0
	global_load_lds_dwordx4 v[144:145], off
	v_lshl_add_u64 v[144:145], s[6:7], 0, v[128:129]
	s_add_i32 m0, s24, 0x2000
	s_nop 0
	global_load_lds_dwordx4 v[144:145], off
	v_lshl_add_u64 v[144:145], v[226:227], 0, s[74:75]
	s_mov_b32 m0, s35
	s_nop 0
	global_load_lds_dwordx4 v[144:145], off
	v_lshl_add_u64 v[144:145], v[228:229], 0, s[74:75]
	s_mov_b32 m0, s36
	s_nop 0
	global_load_lds_dwordx4 v[144:145], off
	s_waitcnt vmcnt(8)
	s_waitcnt lgkmcnt(0)
	s_barrier
	s_waitcnt lgkmcnt(0)
	v_mfma_f32_16x16x32_bf16 v[60:63], v[140:143], v[178:181], v[60:63]
	v_mfma_f32_16x16x32_bf16 v[56:59], v[154:157], v[178:181], v[56:59]
	v_mfma_f32_16x16x32_bf16 v[44:47], v[140:143], v[194:197], v[44:47]
	v_mfma_f32_16x16x32_bf16 v[40:43], v[154:157], v[194:197], v[40:43]
	v_mfma_f32_16x16x32_bf16 v[28:31], v[140:143], v[202:205], v[28:31]
	v_mfma_f32_16x16x32_bf16 v[24:27], v[154:157], v[202:205], v[24:27]
	v_mfma_f32_16x16x32_bf16 v[12:15], v[140:143], v[218:221], v[12:15]
	v_mfma_f32_16x16x32_bf16 v[8:11], v[154:157], v[218:221], v[8:11]
	v_mfma_f32_16x16x32_bf16 v[60:63], v[150:153], v[190:193], v[60:63]
	v_mfma_f32_16x16x32_bf16 v[56:59], v[158:161], v[190:193], v[56:59]
	v_mfma_f32_16x16x32_bf16 v[44:47], v[150:153], v[198:201], v[44:47]
	v_mfma_f32_16x16x32_bf16 v[40:43], v[158:161], v[198:201], v[40:43]
	v_mfma_f32_16x16x32_bf16 v[28:31], v[150:153], v[214:217], v[28:31]
	v_mfma_f32_16x16x32_bf16 v[24:27], v[158:161], v[214:217], v[24:27]
	v_mfma_f32_16x16x32_bf16 v[12:15], v[150:153], v[222:225], v[12:15]
	v_mfma_f32_16x16x32_bf16 v[8:11], v[158:161], v[222:225], v[8:11]
	v_mfma_f32_16x16x32_bf16 v[52:55], v[162:165], v[178:181], v[52:55]
	v_mfma_f32_16x16x32_bf16 v[48:51], v[170:173], v[178:181], v[48:51]
	v_mfma_f32_16x16x32_bf16 v[36:39], v[162:165], v[194:197], v[36:39]
	v_mfma_f32_16x16x32_bf16 v[32:35], v[170:173], v[194:197], v[32:35]
	v_mfma_f32_16x16x32_bf16 v[20:23], v[162:165], v[202:205], v[20:23]
	v_mfma_f32_16x16x32_bf16 v[16:19], v[170:173], v[202:205], v[16:19]
	v_mfma_f32_16x16x32_bf16 v[4:7], v[162:165], v[218:221], v[4:7]
	v_mfma_f32_16x16x32_bf16 v[0:3], v[170:173], v[218:221], v[0:3]
	v_mfma_f32_16x16x32_bf16 v[52:55], v[166:169], v[190:193], v[52:55]
	v_mfma_f32_16x16x32_bf16 v[48:51], v[174:177], v[190:193], v[48:51]
	v_mfma_f32_16x16x32_bf16 v[36:39], v[166:169], v[198:201], v[36:39]
	v_mfma_f32_16x16x32_bf16 v[32:35], v[174:177], v[198:201], v[32:35]
	v_mfma_f32_16x16x32_bf16 v[20:23], v[166:169], v[214:217], v[20:23]
	v_mfma_f32_16x16x32_bf16 v[16:19], v[174:177], v[214:217], v[16:19]
	v_mfma_f32_16x16x32_bf16 v[4:7], v[166:169], v[222:225], v[4:7]
	v_mfma_f32_16x16x32_bf16 v[0:3], v[174:177], v[222:225], v[0:3]
	s_barrier
	s_add_i32 s44, s44, 2
	s_add_u32 s4, s4, 0x100
	s_addc_u32 s5, s5, 0
	s_add_u32 s42, s42, 0x100
	s_addc_u32 s43, s43, 0
	s_cmp_gt_u32 s44, 29
	s_cbranch_scc0 .LBB0_167
	s_and_b64 vcc, exec, s[14:15]
	s_cbranch_vccz .LBB0_170
	s_barrier

; #define PG8_STAGE(bufoff, gbase, voff) do { _Pragma("unroll") for (int _i = 0; _i < 2; ++_i) \
;         __builtin_amdgcn_global_load_lds((const unsigned*)((const char*)(gbase) + (voff)[_i]), (PG8_LAS unsigned*)(lds + (bufoff) + ldsw + _i * 8192), 16, 0, 0); } while (0)
; #define PG8_LDA(dst, b, h) do { _Pragma("unroll") for (int m = 0; m < 4; ++m) _Pragma("unroll") for (int k = 0; k < 2; ++k) dst[m][k] = *(const PG8_LAS bf16x8*)(lds + PG8_SA(b, h) + aoff + m * 2048 + k * 1024); } while (0)
; #define PG8_LDB(dst, b, h) do { _Pragma("unroll") for (int n = 0; n < 2; ++n) _Pragma("unroll") for (int k = 0; k < 2; ++k) dst[n][k] = *(const PG8_LAS bf16x8*)(lds + PG8_SB(b, h) + boff + n * 2048 + k * 1024); } while (0)
; #define PG8_MMA(ai, bj, At, Bt) do { __builtin_amdgcn_s_setprio(1); _Pragma("unroll") for (int m = 0; m < 4; ++m) _Pragma("unroll") for (int n = 0; n < 2; ++n) _Pragma("unroll") for (int k = 0; k < 2; ++k) \
;         acc[ai][bj][m][n] = __builtin_amdgcn_mfma_f32_16x16x32_bf16(Bt[n][k], At[m][k], acc[ai][bj][m][n], 0, 0, 0); __builtin_amdgcn_s_setprio(0); } while (0)
; #define PG8_WAIT_V(n) asm volatile("s_waitcnt vmcnt(" #n ")" ::: "memory")
; #define PG8_WAIT_L(n) asm volatile("s_waitcnt lgkmcnt(" #n ")" ::: "memory")
; #define PG8_BAR __builtin_amdgcn_s_barrier()
; #define PG8_SCHED __builtin_amdgcn_sched_barrier(0)
; template <class Epi, class Sched, bool ALIGN_EPI = false, bool SP2 = false>
; __device__ __forceinline__ void gemm_phase(PG8_LAS unsigned char* lds, const Gemm g, const Sched& S, const Epi& E, const int wid_in) {
;     ...
;             PG8_LDB(B0, 0, 0); PG8_LDB(B1, 0, 1); PG8_SCHED; PG8_LDA(At, 0, 0); PG8_STAGE(PG8_SA(1, 1), a1 + hstep, voffA);
;             PG8_WAIT_V(8); PG8_WAIT_L(0); PG8_BAR; PG8_MMA(0, 0, At, B0); PG8_MMA(0, 1, At, B1); PG8_BAR; PG8_SCHED;
;             PG8_LDA(At, 0, 1); PG8_STAGE(PG8_SB(0, 0), b2, voffB); PG8_STAGE(PG8_SB(0, 1), b2 + hstep, voffB); PG8_STAGE(PG8_SA(0, 0), a2, voffA);
;             PG8_WAIT_V(8); PG8_WAIT_L(0); PG8_BAR; PG8_MMA(1, 0, At, B0); PG8_MMA(1, 1, At, B1); PG8_BAR; PG8_SCHED;
.LBB0_1099:
	s_add_u32 s24, s4, 0x100
	s_addc_u32 s25, s5, 0
	s_add_i32 s55, 0, 0x10000
	s_cmp_eq_u32 s54, 28
	s_cselect_b32 s29, s19, s25
	s_cselect_b32 s28, s50, s24
	s_cselect_b32 s27, s17, s53
	s_cselect_b32 s26, s51, s52
	s_add_i32 s56, 0, 0x14000
	v_add_u32_e32 v88, s55, v205
	v_add_u32_e32 v156, s56, v205
	ds_read_b128 v[72:75], v88
	ds_read_b128 v[80:83], v88 offset:1024
	ds_read_b128 v[84:87], v88 offset:2048
	ds_read_b128 v[88:91], v88 offset:3072
	ds_read_b128 v[144:147], v156
	ds_read_b128 v[148:151], v156 offset:1024
	ds_read_b128 v[152:155], v156 offset:2048
	ds_read_b128 v[156:159], v156 offset:3072
	v_lshl_add_u64 v[180:181], s[4:5], 0, v[192:193]
	s_add_i32 m0, s41, 0xc000
	ds_read_b128 v[160:163], v217
	ds_read_b128 v[164:167], v217 offset:1024
	ds_read_b128 v[168:171], v217 offset:2048
	ds_read_b128 v[172:175], v217 offset:3072
	ds_read_b128 v[176:179], v217 offset:4096
	ds_read_b128 v[196:199], v217 offset:5120
	ds_read_b128 v[200:203], v217 offset:6144
	ds_read_b128 v[218:221], v217 offset:7168
	global_load_lds_dwordx4 v[180:181], off
	v_lshl_add_u64 v[180:181], s[4:5], 0, v[194:195]
	s_add_i32 m0, s41, 0xe000
	s_nop 0
	global_load_lds_dwordx4 v[180:181], off
	s_waitcnt vmcnt(8)
	s_waitcnt lgkmcnt(0)
	s_barrier
	s_waitcnt lgkmcnt(0)
	v_mfma_f32_16x16x32_bf16 v[140:143], v[72:75], v[160:163], v[140:143]
	v_mfma_f32_16x16x32_bf16 v[136:139], v[84:87], v[160:163], v[136:139]
	v_mfma_f32_16x16x32_bf16 v[128:131], v[72:75], v[168:171], v[128:131]
	v_mfma_f32_16x16x32_bf16 v[120:123], v[84:87], v[168:171], v[120:123]
	v_mfma_f32_16x16x32_bf16 v[112:115], v[72:75], v[176:179], v[112:115]
	v_mfma_f32_16x16x32_bf16 v[104:107], v[84:87], v[176:179], v[104:107]
	v_mfma_f32_16x16x32_bf16 v[96:99], v[72:75], v[200:203], v[96:99]
	v_mfma_f32_16x16x32_bf16 v[76:79], v[84:87], v[200:203], v[76:79]
	v_mfma_f32_16x16x32_bf16 v[140:143], v[80:83], v[164:167], v[140:143]
	v_mfma_f32_16x16x32_bf16 v[136:139], v[88:91], v[164:167], v[136:139]
	v_mfma_f32_16x16x32_bf16 v[128:131], v[80:83], v[172:175], v[128:131]
	v_mfma_f32_16x16x32_bf16 v[120:123], v[88:91], v[172:175], v[120:123]
	v_mfma_f32_16x16x32_bf16 v[112:115], v[80:83], v[196:199], v[112:115]
	v_mfma_f32_16x16x32_bf16 v[104:107], v[88:91], v[196:199], v[104:107]
	v_mfma_f32_16x16x32_bf16 v[96:99], v[80:83], v[218:221], v[96:99]
	v_mfma_f32_16x16x32_bf16 v[76:79], v[88:91], v[218:221], v[76:79]
	v_mfma_f32_16x16x32_bf16 v[132:135], v[144:147], v[160:163], v[132:135]
	v_mfma_f32_16x16x32_bf16 v[124:127], v[152:155], v[160:163], v[124:127]
	v_mfma_f32_16x16x32_bf16 v[116:119], v[144:147], v[168:171], v[116:119]
	v_mfma_f32_16x16x32_bf16 v[108:111], v[152:155], v[168:171], v[108:111]
	v_mfma_f32_16x16x32_bf16 v[100:103], v[144:147], v[176:179], v[100:103]
	v_mfma_f32_16x16x32_bf16 v[92:95], v[152:155], v[176:179], v[92:95]
	v_mfma_f32_16x16x32_bf16 v[68:71], v[144:147], v[200:203], v[68:71]
	v_mfma_f32_16x16x32_bf16 v[64:67], v[152:155], v[200:203], v[64:67]
	v_mfma_f32_16x16x32_bf16 v[132:135], v[148:151], v[164:167], v[132:135]
	v_mfma_f32_16x16x32_bf16 v[124:127], v[156:159], v[164:167], v[124:127]
	v_mfma_f32_16x16x32_bf16 v[116:119], v[148:151], v[172:175], v[116:119]
	v_mfma_f32_16x16x32_bf16 v[108:111], v[156:159], v[172:175], v[108:111]
	v_mfma_f32_16x16x32_bf16 v[100:103], v[148:151], v[196:199], v[100:103]
	v_mfma_f32_16x16x32_bf16 v[92:95], v[156:159], v[196:199], v[92:95]
	v_mfma_f32_16x16x32_bf16 v[68:71], v[148:151], v[218:221], v[68:71]
	v_mfma_f32_16x16x32_bf16 v[64:67], v[156:159], v[218:221], v[64:67]
	s_barrier
	s_add_i32 s4, s55, s40
	v_lshl_add_u64 v[180:181], s[26:27], 0, v[182:183]
	s_mov_b32 m0, s4
	ds_read_b128 v[160:163], v217 offset:16384
	ds_read_b128 v[164:167], v217 offset:17408
	ds_read_b128 v[168:171], v217 offset:18432
	ds_read_b128 v[172:175], v217 offset:19456
	ds_read_b128 v[176:179], v217 offset:20480
	ds_read_b128 v[196:199], v217 offset:21504
	ds_read_b128 v[200:203], v217 offset:22528
	ds_read_b128 v[218:221], v217 offset:23552
	global_load_lds_dwordx4 v[180:181], off
	s_add_i32 m0, s4, 0x2000
	s_add_u32 s4, s26, 0x80000
	v_lshl_add_u64 v[188:189], s[26:27], 0, v[190:191]
	s_addc_u32 s5, s27, 0
	s_add_i32 s55, s56, s40
	global_load_lds_dwordx4 v[188:189], off
	v_lshl_add_u64 v[222:223], s[4:5], 0, v[182:183]
	s_mov_b32 m0, s55
	v_lshl_add_u64 v[224:225], s[28:29], 0, v[190:191]
	global_load_lds_dwordx4 v[222:223], off
	v_lshl_add_u64 v[222:223], s[4:5], 0, v[190:191]
	s_add_i32 m0, s55, 0x2000
	s_nop 0
	global_load_lds_dwordx4 v[222:223], off
	v_lshl_add_u64 v[222:223], s[28:29], 0, v[182:183]
	s_mov_b32 m0, s41
	s_nop 0
	global_load_lds_dwordx4 v[222:223], off
	s_mov_b32 m0, s42
	s_nop 0
	global_load_lds_dwordx4 v[224:225], off
	s_waitcnt vmcnt(8)
	s_waitcnt lgkmcnt(0)
	s_barrier
; #define PG8_STAGE(bufoff, gbase, voff) do { _Pragma("unroll") for (int _i = 0; _i < 2; ++_i) \
;         __builtin_amdgcn_global_load_lds((const unsigned*)((const char*)(gbase) + (voff)[_i]), (PG8_LAS unsigned*)(lds + (bufoff) + ldsw + _i * 8192), 16, 0, 0); } while (0)
; #define PG8_LDA(dst, b, h) do { _Pragma("unroll") for (int m = 0; m < 4; ++m) _Pragma("unroll") for (int k = 0; k < 2; ++k) dst[m][k] = *(const PG8_LAS bf16x8*)(lds + PG8_SA(b, h) + aoff + m * 2048 + k * 1024); } while (0)
; #define PG8_LDB(dst, b, h) do { _Pragma("unroll") for (int n = 0; n < 2; ++n) _Pragma("unroll") for (int k = 0; k < 2; ++k) dst[n][k] = *(const PG8_LAS bf16x8*)(lds + PG8_SB(b, h) + boff + n * 2048 + k * 1024); } while (0)
; #define PG8_MMA(ai, bj, At, Bt) do { __builtin_amdgcn_s_setprio(1); _Pragma("unroll") for (int m = 0; m < 4; ++m) _Pragma("unroll") for (int n = 0; n < 2; ++n) _Pragma("unroll") for (int k = 0; k < 2; ++k) \
;         acc[ai][bj][m][n] = __builtin_amdgcn_mfma_f32_16x16x32_bf16(Bt[n][k], At[m][k], acc[ai][bj][m][n], 0, 0, 0); __builtin_amdgcn_s_setprio(0); } while (0)
; #define PG8_WAIT_V(n) asm volatile("s_waitcnt vmcnt(" #n ")" ::: "memory")
; #define PG8_WAIT_L(n) asm volatile("s_waitcnt lgkmcnt(" #n ")" ::: "memory")
; #define PG8_BAR __builtin_amdgcn_s_barrier()
; #define PG8_SCHED __builtin_amdgcn_sched_barrier(0)
; template <class Epi, class Sched, bool ALIGN_EPI = false, bool SP2 = false>
; __device__ __forceinline__ void gemm_phase(PG8_LAS unsigned char* lds, const Gemm g, const Sched& S, const Epi& E, const int wid_in) {
;     ...
;             PG8_WAIT_V(8); PG8_WAIT_L(0); PG8_BAR; PG8_MMA(1, 0, At, B0); PG8_MMA(1, 1, At, B1); PG8_BAR; PG8_SCHED;
;             PG8_LDB(B0, 1, 0); PG8_LDB(B1, 1, 1); PG8_SCHED; PG8_LDA(At, 1, 0); PG8_STAGE(PG8_SA(0, 1), a2 + hstep, voffA);
;             PG8_WAIT_V(8); PG8_WAIT_L(0); PG8_BAR; PG8_MMA(0, 0, At, B0); PG8_MMA(0, 1, At, B1); PG8_BAR; PG8_SCHED;
	s_waitcnt lgkmcnt(0)
	v_mfma_f32_16x16x32_bf16 v[60:63], v[72:75], v[160:163], v[60:63]
	v_mfma_f32_16x16x32_bf16 v[56:59], v[84:87], v[160:163], v[56:59]
	v_mfma_f32_16x16x32_bf16 v[48:51], v[72:75], v[168:171], v[48:51]
	v_mfma_f32_16x16x32_bf16 v[40:43], v[84:87], v[168:171], v[40:43]
	v_mfma_f32_16x16x32_bf16 v[32:35], v[72:75], v[176:179], v[32:35]
	v_mfma_f32_16x16x32_bf16 v[24:27], v[84:87], v[176:179], v[24:27]
	v_mfma_f32_16x16x32_bf16 v[16:19], v[72:75], v[200:203], v[16:19]
	v_mfma_f32_16x16x32_bf16 v[8:11], v[84:87], v[200:203], v[8:11]
	v_mfma_f32_16x16x32_bf16 v[60:63], v[80:83], v[164:167], v[60:63]
	v_mfma_f32_16x16x32_bf16 v[56:59], v[88:91], v[164:167], v[56:59]
	v_mfma_f32_16x16x32_bf16 v[48:51], v[80:83], v[172:175], v[48:51]
	v_mfma_f32_16x16x32_bf16 v[40:43], v[88:91], v[172:175], v[40:43]
	v_mfma_f32_16x16x32_bf16 v[32:35], v[80:83], v[196:199], v[32:35]
	v_mfma_f32_16x16x32_bf16 v[24:27], v[88:91], v[196:199], v[24:27]
	v_mfma_f32_16x16x32_bf16 v[16:19], v[80:83], v[218:221], v[16:19]
	v_mfma_f32_16x16x32_bf16 v[8:11], v[88:91], v[218:221], v[8:11]
	v_mfma_f32_16x16x32_bf16 v[52:55], v[144:147], v[160:163], v[52:55]
	v_mfma_f32_16x16x32_bf16 v[44:47], v[152:155], v[160:163], v[44:47]
	v_mfma_f32_16x16x32_bf16 v[36:39], v[144:147], v[168:171], v[36:39]
	v_mfma_f32_16x16x32_bf16 v[28:31], v[152:155], v[168:171], v[28:31]
	v_mfma_f32_16x16x32_bf16 v[20:23], v[144:147], v[176:179], v[20:23]
	v_mfma_f32_16x16x32_bf16 v[12:15], v[152:155], v[176:179], v[12:15]
	v_mfma_f32_16x16x32_bf16 v[4:7], v[144:147], v[200:203], v[4:7]
	v_mfma_f32_16x16x32_bf16 v[0:3], v[152:155], v[200:203], v[0:3]
	v_mfma_f32_16x16x32_bf16 v[52:55], v[148:151], v[164:167], v[52:55]
	v_mfma_f32_16x16x32_bf16 v[44:47], v[156:159], v[164:167], v[44:47]
	v_mfma_f32_16x16x32_bf16 v[36:39], v[148:151], v[172:175], v[36:39]
	v_mfma_f32_16x16x32_bf16 v[28:31], v[156:159], v[172:175], v[28:31]
	v_mfma_f32_16x16x32_bf16 v[20:23], v[148:151], v[196:199], v[20:23]
	v_mfma_f32_16x16x32_bf16 v[12:15], v[156:159], v[196:199], v[12:15]
	v_mfma_f32_16x16x32_bf16 v[4:7], v[148:151], v[218:221], v[4:7]
	v_mfma_f32_16x16x32_bf16 v[0:3], v[156:159], v[218:221], v[0:3]
	s_barrier
	s_add_i32 s55, 0, 0x18000
	s_add_i32 s56, 0, 0x1c000
	v_add_u32_e32 v88, s55, v205
	v_add_u32_e32 v156, s56, v205
	ds_read_b128 v[72:75], v88
	ds_read_b128 v[80:83], v88 offset:1024
	ds_read_b128 v[84:87], v88 offset:2048
	ds_read_b128 v[88:91], v88 offset:3072
	ds_read_b128 v[144:147], v156
	ds_read_b128 v[148:151], v156 offset:1024
	ds_read_b128 v[152:155], v156 offset:2048
	ds_read_b128 v[156:159], v156 offset:3072
	s_add_u32 s4, s28, 0x80000
	s_addc_u32 s5, s29, 0
	s_mov_b32 m0, s43
	v_lshl_add_u64 v[226:227], s[4:5], 0, v[182:183]
	ds_read_b128 v[160:163], v217 offset:32768
	ds_read_b128 v[164:167], v217 offset:33792
	ds_read_b128 v[168:171], v217 offset:34816
	ds_read_b128 v[172:175], v217 offset:35840
	ds_read_b128 v[176:179], v217 offset:36864
	ds_read_b128 v[196:199], v217 offset:37888
	ds_read_b128 v[200:203], v217 offset:38912
	ds_read_b128 v[218:221], v217 offset:39936
	global_load_lds_dwordx4 v[226:227], off
	v_lshl_add_u64 v[226:227], s[4:5], 0, v[190:191]
	s_mov_b32 m0, s44
	s_nop 0
	global_load_lds_dwordx4 v[226:227], off
	s_waitcnt vmcnt(8)
	s_waitcnt lgkmcnt(0)
	s_barrier
	s_waitcnt lgkmcnt(0)
	v_mfma_f32_16x16x32_bf16 v[140:143], v[72:75], v[160:163], v[140:143]
	v_mfma_f32_16x16x32_bf16 v[136:139], v[84:87], v[160:163], v[136:139]
	v_mfma_f32_16x16x32_bf16 v[128:131], v[72:75], v[168:171], v[128:131]
	v_mfma_f32_16x16x32_bf16 v[120:123], v[84:87], v[168:171], v[120:123]
	v_mfma_f32_16x16x32_bf16 v[112:115], v[72:75], v[176:179], v[112:115]
	v_mfma_f32_16x16x32_bf16 v[104:107], v[84:87], v[176:179], v[104:107]
	v_mfma_f32_16x16x32_bf16 v[96:99], v[72:75], v[200:203], v[96:99]
	v_mfma_f32_16x16x32_bf16 v[76:79], v[84:87], v[200:203], v[76:79]
	v_mfma_f32_16x16x32_bf16 v[140:143], v[80:83], v[164:167], v[140:143]
	v_mfma_f32_16x16x32_bf16 v[136:139], v[88:91], v[164:167], v[136:139]
	v_mfma_f32_16x16x32_bf16 v[128:131], v[80:83], v[172:175], v[128:131]
	v_mfma_f32_16x16x32_bf16 v[120:123], v[88:91], v[172:175], v[120:123]
	v_mfma_f32_16x16x32_bf16 v[112:115], v[80:83], v[196:199], v[112:115]
	v_mfma_f32_16x16x32_bf16 v[104:107], v[88:91], v[196:199], v[104:107]
	v_mfma_f32_16x16x32_bf16 v[96:99], v[80:83], v[218:221], v[96:99]
	v_mfma_f32_16x16x32_bf16 v[76:79], v[88:91], v[218:221], v[76:79]
	v_mfma_f32_16x16x32_bf16 v[132:135], v[144:147], v[160:163], v[132:135]
	v_mfma_f32_16x16x32_bf16 v[124:127], v[152:155], v[160:163], v[124:127]
	v_mfma_f32_16x16x32_bf16 v[116:119], v[144:147], v[168:171], v[116:119]
	v_mfma_f32_16x16x32_bf16 v[108:111], v[152:155], v[168:171], v[108:111]
	v_mfma_f32_16x16x32_bf16 v[100:103], v[144:147], v[176:179], v[100:103]
	v_mfma_f32_16x16x32_bf16 v[92:95], v[152:155], v[176:179], v[92:95]
	v_mfma_f32_16x16x32_bf16 v[68:71], v[144:147], v[200:203], v[68:71]
	v_mfma_f32_16x16x32_bf16 v[64:67], v[152:155], v[200:203], v[64:67]
	v_mfma_f32_16x16x32_bf16 v[132:135], v[148:151], v[164:167], v[132:135]
	v_mfma_f32_16x16x32_bf16 v[124:127], v[156:159], v[164:167], v[124:127]
	v_mfma_f32_16x16x32_bf16 v[116:119], v[148:151], v[172:175], v[116:119]
	v_mfma_f32_16x16x32_bf16 v[108:111], v[156:159], v[172:175], v[108:111]
	v_mfma_f32_16x16x32_bf16 v[100:103], v[148:151], v[196:199], v[100:103]
	v_mfma_f32_16x16x32_bf16 v[92:95], v[156:159], v[196:199], v[92:95]
	v_mfma_f32_16x16x32_bf16 v[68:71], v[148:151], v[218:221], v[68:71]
	v_mfma_f32_16x16x32_bf16 v[64:67], v[156:159], v[218:221], v[64:67]
	s_barrier
; #define PG8_STAGE(bufoff, gbase, voff) do { _Pragma("unroll") for (int _i = 0; _i < 2; ++_i) \
;         __builtin_amdgcn_global_load_lds((const unsigned*)((const char*)(gbase) + (voff)[_i]), (PG8_LAS unsigned*)(lds + (bufoff) + ldsw + _i * 8192), 16, 0, 0); } while (0)
; #define PG8_LDA(dst, b, h) do { _Pragma("unroll") for (int m = 0; m < 4; ++m) _Pragma("unroll") for (int k = 0; k < 2; ++k) dst[m][k] = *(const PG8_LAS bf16x8*)(lds + PG8_SA(b, h) + aoff + m * 2048 + k * 1024); } while (0)
; #define PG8_MMA(ai, bj, At, Bt) do { __builtin_amdgcn_s_setprio(1); _Pragma("unroll") for (int m = 0; m < 4; ++m) _Pragma("unroll") for (int n = 0; n < 2; ++n) _Pragma("unroll") for (int k = 0; k < 2; ++k) \
;         acc[ai][bj][m][n] = __builtin_amdgcn_mfma_f32_16x16x32_bf16(Bt[n][k], At[m][k], acc[ai][bj][m][n], 0, 0, 0); __builtin_amdgcn_s_setprio(0); } while (0)
; #define PG8_WAIT_V(n) asm volatile("s_waitcnt vmcnt(" #n ")" ::: "memory")
; #define PG8_WAIT_L(n) asm volatile("s_waitcnt lgkmcnt(" #n ")" ::: "memory")
; #define PG8_BAR __builtin_amdgcn_s_barrier()
; #define PG8_SCHED __builtin_amdgcn_sched_barrier(0)
; template <class Epi, class Sched, bool ALIGN_EPI = false, bool SP2 = false>
; __device__ __forceinline__ void gemm_phase(PG8_LAS unsigned char* lds, const Gemm g, const Sched& S, const Epi& E, const int wid_in) {
;     ...
;         for (int t = 0; t < nt; t += 2) {
;             const bool last = (t == nt - 2);
;     ...
;             PG8_LDA(At, 1, 1); PG8_STAGE(PG8_SB(1, 0), b3, voffB); PG8_STAGE(PG8_SB(1, 1), b3 + hstep, voffB); PG8_STAGE(PG8_SA(1, 0), a3, voffA);
;             PG8_WAIT_V(8); PG8_WAIT_L(0); PG8_BAR; PG8_MMA(1, 0, At, B0); PG8_MMA(1, 1, At, B1); PG8_BAR; PG8_SCHED;
	s_add_i32 s4, s55, s40
	v_lshl_add_u64 v[180:181], v[180:181], 0, s[74:75]
	s_mov_b32 m0, s4
	ds_read_b128 v[160:163], v217 offset:49152
	ds_read_b128 v[164:167], v217 offset:50176
	ds_read_b128 v[168:171], v217 offset:51200
	ds_read_b128 v[172:175], v217 offset:52224
	ds_read_b128 v[176:179], v217 offset:53248
	ds_read_b128 v[196:199], v217 offset:54272
	ds_read_b128 v[200:203], v217 offset:55296
	ds_read_b128 v[218:221], v217 offset:56320
	global_load_lds_dwordx4 v[180:181], off
	s_add_i32 m0, s4, 0x2000
	s_add_u32 s4, s26, 0x80080
	v_lshl_add_u64 v[180:181], v[188:189], 0, s[74:75]
	s_addc_u32 s5, s27, 0
	s_add_i32 s26, s56, s40
	global_load_lds_dwordx4 v[180:181], off
	v_lshl_add_u64 v[180:181], s[4:5], 0, v[182:183]
	s_mov_b32 m0, s26
	s_nop 0
	global_load_lds_dwordx4 v[180:181], off
	v_lshl_add_u64 v[180:181], s[4:5], 0, v[190:191]
	s_add_i32 m0, s26, 0x2000
	s_nop 0
	global_load_lds_dwordx4 v[180:181], off
	v_lshl_add_u64 v[180:181], v[222:223], 0, s[74:75]
	s_mov_b32 m0, s45
	s_nop 0
	global_load_lds_dwordx4 v[180:181], off
	v_lshl_add_u64 v[180:181], v[224:225], 0, s[74:75]
	s_mov_b32 m0, s46
	s_nop 0
	global_load_lds_dwordx4 v[180:181], off
	s_waitcnt vmcnt(8)
	s_waitcnt lgkmcnt(0)
	s_barrier
	s_waitcnt lgkmcnt(0)
	v_mfma_f32_16x16x32_bf16 v[60:63], v[72:75], v[160:163], v[60:63]
	v_mfma_f32_16x16x32_bf16 v[56:59], v[84:87], v[160:163], v[56:59]
	v_mfma_f32_16x16x32_bf16 v[48:51], v[72:75], v[168:171], v[48:51]
	v_mfma_f32_16x16x32_bf16 v[40:43], v[84:87], v[168:171], v[40:43]
	v_mfma_f32_16x16x32_bf16 v[32:35], v[72:75], v[176:179], v[32:35]
	v_mfma_f32_16x16x32_bf16 v[24:27], v[84:87], v[176:179], v[24:27]
	v_mfma_f32_16x16x32_bf16 v[16:19], v[72:75], v[200:203], v[16:19]
	v_mfma_f32_16x16x32_bf16 v[8:11], v[84:87], v[200:203], v[8:11]
	v_mfma_f32_16x16x32_bf16 v[60:63], v[80:83], v[164:167], v[60:63]
	v_mfma_f32_16x16x32_bf16 v[56:59], v[88:91], v[164:167], v[56:59]
	v_mfma_f32_16x16x32_bf16 v[48:51], v[80:83], v[172:175], v[48:51]
	v_mfma_f32_16x16x32_bf16 v[40:43], v[88:91], v[172:175], v[40:43]
	v_mfma_f32_16x16x32_bf16 v[32:35], v[80:83], v[196:199], v[32:35]
	v_mfma_f32_16x16x32_bf16 v[24:27], v[88:91], v[196:199], v[24:27]
	v_mfma_f32_16x16x32_bf16 v[16:19], v[80:83], v[218:221], v[16:19]
	v_mfma_f32_16x16x32_bf16 v[8:11], v[88:91], v[218:221], v[8:11]
	v_mfma_f32_16x16x32_bf16 v[52:55], v[144:147], v[160:163], v[52:55]
	v_mfma_f32_16x16x32_bf16 v[44:47], v[152:155], v[160:163], v[44:47]
	v_mfma_f32_16x16x32_bf16 v[36:39], v[144:147], v[168:171], v[36:39]
	v_mfma_f32_16x16x32_bf16 v[28:31], v[152:155], v[168:171], v[28:31]
	v_mfma_f32_16x16x32_bf16 v[20:23], v[144:147], v[176:179], v[20:23]
	v_mfma_f32_16x16x32_bf16 v[12:15], v[152:155], v[176:179], v[12:15]
	v_mfma_f32_16x16x32_bf16 v[4:7], v[144:147], v[200:203], v[4:7]
	v_mfma_f32_16x16x32_bf16 v[0:3], v[152:155], v[200:203], v[0:3]
	v_mfma_f32_16x16x32_bf16 v[52:55], v[148:151], v[164:167], v[52:55]
	v_mfma_f32_16x16x32_bf16 v[44:47], v[156:159], v[164:167], v[44:47]
	v_mfma_f32_16x16x32_bf16 v[36:39], v[148:151], v[172:175], v[36:39]
	v_mfma_f32_16x16x32_bf16 v[28:31], v[156:159], v[172:175], v[28:31]
	v_mfma_f32_16x16x32_bf16 v[20:23], v[148:151], v[196:199], v[20:23]
	v_mfma_f32_16x16x32_bf16 v[12:15], v[156:159], v[196:199], v[12:15]
	v_mfma_f32_16x16x32_bf16 v[4:7], v[148:151], v[218:221], v[4:7]
	v_mfma_f32_16x16x32_bf16 v[0:3], v[156:159], v[218:221], v[0:3]
	s_barrier
	s_add_i32 s54, s54, 2
	s_add_u32 s52, s52, 0x100
	s_addc_u32 s53, s53, 0
	s_cmp_gt_u32 s54, 29
	s_mov_b64 s[4:5], s[24:25]
	s_cbranch_scc0 .LBB0_1099
	s_and_b64 vcc, exec, s[14:15]
	s_cbranch_vccz .LBB0_1102
	s_barrier

; #define PG8_STAGE(bufoff, gbase, voff) do { _Pragma("unroll") for (int _i = 0; _i < 2; ++_i) \
;         __builtin_amdgcn_global_load_lds((const unsigned*)((const char*)(gbase) + (voff)[_i]), (PG8_LAS unsigned*)(lds + (bufoff) + ldsw + _i * 8192), 16, 0, 0); } while (0)
; #define PG8_LDA(dst, b, h) do { _Pragma("unroll") for (int m = 0; m < 4; ++m) _Pragma("unroll") for (int k = 0; k < 2; ++k) dst[m][k] = *(const PG8_LAS bf16x8*)(lds + PG8_SA(b, h) + aoff + m * 2048 + k * 1024); } while (0)
; #define PG8_LDB(dst, b, h) do { _Pragma("unroll") for (int n = 0; n < 2; ++n) _Pragma("unroll") for (int k = 0; k < 2; ++k) dst[n][k] = *(const PG8_LAS bf16x8*)(lds + PG8_SB(b, h) + boff + n * 2048 + k * 1024); } while (0)
; #define PG8_MMA(ai, bj, At, Bt) do { __builtin_amdgcn_s_setprio(1); _Pragma("unroll") for (int m = 0; m < 4; ++m) _Pragma("unroll") for (int n = 0; n < 2; ++n) _Pragma("unroll") for (int k = 0; k < 2; ++k) \
;         acc[ai][bj][m][n] = __builtin_amdgcn_mfma_f32_16x16x32_bf16(Bt[n][k], At[m][k], acc[ai][bj][m][n], 0, 0, 0); __builtin_amdgcn_s_setprio(0); } while (0)
; #define PG8_WAIT_V(n) asm volatile("s_waitcnt vmcnt(" #n ")" ::: "memory")
; #define PG8_WAIT_L(n) asm volatile("s_waitcnt lgkmcnt(" #n ")" ::: "memory")
; #define PG8_BAR __builtin_amdgcn_s_barrier()
; #define PG8_SCHED __builtin_amdgcn_sched_barrier(0)
; template <class Epi, class Sched, bool ALIGN_EPI = false, bool SP2 = false>
; __device__ __forceinline__ void gemm_phase(PG8_LAS unsigned char* lds, const Gemm g, const Sched& S, const Epi& E, const int wid_in) {
;     ...
;             PG8_LDB(B0, 0, 0); PG8_LDB(B1, 0, 1); PG8_SCHED; PG8_LDA(At, 0, 0); PG8_STAGE(PG8_SA(1, 1), a1 + hstep, voffA);
;             PG8_WAIT_V(8); PG8_WAIT_L(0); PG8_BAR; PG8_MMA(0, 0, At, B0); PG8_MMA(0, 1, At, B1); PG8_BAR; PG8_SCHED;
;             PG8_LDA(At, 0, 1); PG8_STAGE(PG8_SB(0, 0), b2, voffB); PG8_STAGE(PG8_SB(0, 1), b2 + hstep, voffB); PG8_STAGE(PG8_SA(0, 0), a2, voffA);
;             PG8_WAIT_V(8); PG8_WAIT_L(0); PG8_BAR; PG8_MMA(1, 0, At, B0); PG8_MMA(1, 1, At, B1); PG8_BAR; PG8_SCHED;
.LBB0_1212:
	s_add_u32 s18, s4, 0xfff80080
	s_addc_u32 s19, s5, -1
	s_add_i32 s48, 0, 0x10000
	s_cmp_eq_u32 s47, 28
	s_cselect_b32 s21, s13, s19
	s_cselect_b32 s20, s43, s18
	s_cselect_b32 s19, s11, s46
	s_cselect_b32 s18, s44, s45
	s_add_i32 s50, 0, 0x14000
	v_add_u32_e32 v154, s48, v147
	v_add_u32_e32 v170, s50, v147
	ds_read_b128 v[138:141], v154
	ds_read_b128 v[142:145], v154 offset:1024
	ds_read_b128 v[150:153], v154 offset:2048
	ds_read_b128 v[154:157], v154 offset:3072
	ds_read_b128 v[158:161], v170
	ds_read_b128 v[162:165], v170 offset:1024
	ds_read_b128 v[166:169], v170 offset:2048
	ds_read_b128 v[170:173], v170 offset:3072
	v_lshl_add_u64 v[204:205], s[4:5], 0, v[134:135]
	s_add_i32 m0, s26, 0xc000
	ds_read_b128 v[174:177], v149
	ds_read_b128 v[178:181], v149 offset:1024
	ds_read_b128 v[188:191], v149 offset:2048
	ds_read_b128 v[192:195], v149 offset:3072
	ds_read_b128 v[196:199], v149 offset:4096
	ds_read_b128 v[200:203], v149 offset:5120
	ds_read_b128 v[214:217], v149 offset:6144
	ds_read_b128 v[218:221], v149 offset:7168
	global_load_lds_dwordx4 v[204:205], off
	v_lshl_add_u64 v[204:205], s[4:5], 0, v[136:137]
	s_add_i32 m0, s26, 0xe000
	s_nop 0
	global_load_lds_dwordx4 v[204:205], off
	s_waitcnt vmcnt(8)
	s_waitcnt lgkmcnt(0)
	s_barrier
	s_waitcnt lgkmcnt(0)
	v_mfma_f32_16x16x32_bf16 v[124:127], v[138:141], v[174:177], v[124:127]
	v_mfma_f32_16x16x32_bf16 v[120:123], v[150:153], v[174:177], v[120:123]
	v_mfma_f32_16x16x32_bf16 v[108:111], v[138:141], v[188:191], v[108:111]
	v_mfma_f32_16x16x32_bf16 v[104:107], v[150:153], v[188:191], v[104:107]
	v_mfma_f32_16x16x32_bf16 v[92:95], v[138:141], v[196:199], v[92:95]
	v_mfma_f32_16x16x32_bf16 v[88:91], v[150:153], v[196:199], v[88:91]
	v_mfma_f32_16x16x32_bf16 v[76:79], v[138:141], v[214:217], v[76:79]
	v_mfma_f32_16x16x32_bf16 v[72:75], v[150:153], v[214:217], v[72:75]
	v_mfma_f32_16x16x32_bf16 v[124:127], v[142:145], v[178:181], v[124:127]
	v_mfma_f32_16x16x32_bf16 v[120:123], v[154:157], v[178:181], v[120:123]
	v_mfma_f32_16x16x32_bf16 v[108:111], v[142:145], v[192:195], v[108:111]
	v_mfma_f32_16x16x32_bf16 v[104:107], v[154:157], v[192:195], v[104:107]
	v_mfma_f32_16x16x32_bf16 v[92:95], v[142:145], v[200:203], v[92:95]
	v_mfma_f32_16x16x32_bf16 v[88:91], v[154:157], v[200:203], v[88:91]
	v_mfma_f32_16x16x32_bf16 v[76:79], v[142:145], v[218:221], v[76:79]
	v_mfma_f32_16x16x32_bf16 v[72:75], v[154:157], v[218:221], v[72:75]
	v_mfma_f32_16x16x32_bf16 v[116:119], v[158:161], v[174:177], v[116:119]
	v_mfma_f32_16x16x32_bf16 v[112:115], v[166:169], v[174:177], v[112:115]
	v_mfma_f32_16x16x32_bf16 v[100:103], v[158:161], v[188:191], v[100:103]
	v_mfma_f32_16x16x32_bf16 v[96:99], v[166:169], v[188:191], v[96:99]
	v_mfma_f32_16x16x32_bf16 v[84:87], v[158:161], v[196:199], v[84:87]
	v_mfma_f32_16x16x32_bf16 v[80:83], v[166:169], v[196:199], v[80:83]
	v_mfma_f32_16x16x32_bf16 v[68:71], v[158:161], v[214:217], v[68:71]
	v_mfma_f32_16x16x32_bf16 v[64:67], v[166:169], v[214:217], v[64:67]
	v_mfma_f32_16x16x32_bf16 v[116:119], v[162:165], v[178:181], v[116:119]
	v_mfma_f32_16x16x32_bf16 v[112:115], v[170:173], v[178:181], v[112:115]
	v_mfma_f32_16x16x32_bf16 v[100:103], v[162:165], v[192:195], v[100:103]
	v_mfma_f32_16x16x32_bf16 v[96:99], v[170:173], v[192:195], v[96:99]
	v_mfma_f32_16x16x32_bf16 v[84:87], v[162:165], v[200:203], v[84:87]
	v_mfma_f32_16x16x32_bf16 v[80:83], v[170:173], v[200:203], v[80:83]
	v_mfma_f32_16x16x32_bf16 v[68:71], v[162:165], v[218:221], v[68:71]
	v_mfma_f32_16x16x32_bf16 v[64:67], v[170:173], v[218:221], v[64:67]
	s_barrier
	s_add_i32 s48, s48, s25
	v_lshl_add_u64 v[204:205], s[18:19], 0, v[182:183]
	s_mov_b32 m0, s48
	ds_read_b128 v[174:177], v149 offset:16384
	ds_read_b128 v[178:181], v149 offset:17408
	ds_read_b128 v[188:191], v149 offset:18432
	ds_read_b128 v[192:195], v149 offset:19456
	ds_read_b128 v[196:199], v149 offset:20480
	ds_read_b128 v[200:203], v149 offset:21504
	ds_read_b128 v[214:217], v149 offset:22528
	ds_read_b128 v[218:221], v149 offset:23552
	global_load_lds_dwordx4 v[204:205], off
	s_add_i32 m0, s48, 0x2000
	s_add_u32 s48, s18, 0x80000
	v_lshl_add_u64 v[222:223], s[18:19], 0, v[128:129]
	s_addc_u32 s49, s19, 0
	s_add_i32 s50, s50, s25
	global_load_lds_dwordx4 v[222:223], off
	v_lshl_add_u64 v[224:225], s[48:49], 0, v[182:183]
	s_mov_b32 m0, s50
	v_lshl_add_u64 v[226:227], s[20:21], 0, v[130:131]
	global_load_lds_dwordx4 v[224:225], off
	v_lshl_add_u64 v[224:225], s[48:49], 0, v[128:129]
	s_add_i32 m0, s50, 0x2000
	s_nop 0
	global_load_lds_dwordx4 v[224:225], off
	v_lshl_add_u64 v[224:225], s[20:21], 0, v[132:133]
	s_mov_b32 m0, s26
	s_nop 0
	global_load_lds_dwordx4 v[224:225], off
	s_mov_b32 m0, s27
	s_nop 0
	global_load_lds_dwordx4 v[226:227], off
	s_waitcnt vmcnt(8)
	s_waitcnt lgkmcnt(0)
	s_barrier
; #define PG8_STAGE(bufoff, gbase, voff) do { _Pragma("unroll") for (int _i = 0; _i < 2; ++_i) \
;         __builtin_amdgcn_global_load_lds((const unsigned*)((const char*)(gbase) + (voff)[_i]), (PG8_LAS unsigned*)(lds + (bufoff) + ldsw + _i * 8192), 16, 0, 0); } while (0)
; #define PG8_LDA(dst, b, h) do { _Pragma("unroll") for (int m = 0; m < 4; ++m) _Pragma("unroll") for (int k = 0; k < 2; ++k) dst[m][k] = *(const PG8_LAS bf16x8*)(lds + PG8_SA(b, h) + aoff + m * 2048 + k * 1024); } while (0)
; #define PG8_LDB(dst, b, h) do { _Pragma("unroll") for (int n = 0; n < 2; ++n) _Pragma("unroll") for (int k = 0; k < 2; ++k) dst[n][k] = *(const PG8_LAS bf16x8*)(lds + PG8_SB(b, h) + boff + n * 2048 + k * 1024); } while (0)
; #define PG8_MMA(ai, bj, At, Bt) do { __builtin_amdgcn_s_setprio(1); _Pragma("unroll") for (int m = 0; m < 4; ++m) _Pragma("unroll") for (int n = 0; n < 2; ++n) _Pragma("unroll") for (int k = 0; k < 2; ++k) \
;         acc[ai][bj][m][n] = __builtin_amdgcn_mfma_f32_16x16x32_bf16(Bt[n][k], At[m][k], acc[ai][bj][m][n], 0, 0, 0); __builtin_amdgcn_s_setprio(0); } while (0)
; #define PG8_WAIT_V(n) asm volatile("s_waitcnt vmcnt(" #n ")" ::: "memory")
; #define PG8_WAIT_L(n) asm volatile("s_waitcnt lgkmcnt(" #n ")" ::: "memory")
; #define PG8_BAR __builtin_amdgcn_s_barrier()
; #define PG8_SCHED __builtin_amdgcn_sched_barrier(0)
; template <class Epi, class Sched, bool ALIGN_EPI = false, bool SP2 = false>
; __device__ __forceinline__ void gemm_phase(PG8_LAS unsigned char* lds, const Gemm g, const Sched& S, const Epi& E, const int wid_in) {
;     ...
;             PG8_WAIT_V(8); PG8_WAIT_L(0); PG8_BAR; PG8_MMA(1, 0, At, B0); PG8_MMA(1, 1, At, B1); PG8_BAR; PG8_SCHED;
;             PG8_LDB(B0, 1, 0); PG8_LDB(B1, 1, 1); PG8_SCHED; PG8_LDA(At, 1, 0); PG8_STAGE(PG8_SA(0, 1), a2 + hstep, voffA);
;             PG8_WAIT_V(8); PG8_WAIT_L(0); PG8_BAR; PG8_MMA(0, 0, At, B0); PG8_MMA(0, 1, At, B1); PG8_BAR; PG8_SCHED;
	s_waitcnt lgkmcnt(0)
	v_mfma_f32_16x16x32_bf16 v[60:63], v[138:141], v[174:177], v[60:63]
	v_mfma_f32_16x16x32_bf16 v[56:59], v[150:153], v[174:177], v[56:59]
	v_mfma_f32_16x16x32_bf16 v[44:47], v[138:141], v[188:191], v[44:47]
	v_mfma_f32_16x16x32_bf16 v[40:43], v[150:153], v[188:191], v[40:43]
	v_mfma_f32_16x16x32_bf16 v[28:31], v[138:141], v[196:199], v[28:31]
	v_mfma_f32_16x16x32_bf16 v[24:27], v[150:153], v[196:199], v[24:27]
	v_mfma_f32_16x16x32_bf16 v[12:15], v[138:141], v[214:217], v[12:15]
	v_mfma_f32_16x16x32_bf16 v[8:11], v[150:153], v[214:217], v[8:11]
	v_mfma_f32_16x16x32_bf16 v[60:63], v[142:145], v[178:181], v[60:63]
	v_mfma_f32_16x16x32_bf16 v[56:59], v[154:157], v[178:181], v[56:59]
	v_mfma_f32_16x16x32_bf16 v[44:47], v[142:145], v[192:195], v[44:47]
	v_mfma_f32_16x16x32_bf16 v[40:43], v[154:157], v[192:195], v[40:43]
	v_mfma_f32_16x16x32_bf16 v[28:31], v[142:145], v[200:203], v[28:31]
	v_mfma_f32_16x16x32_bf16 v[24:27], v[154:157], v[200:203], v[24:27]
	v_mfma_f32_16x16x32_bf16 v[12:15], v[142:145], v[218:221], v[12:15]
	v_mfma_f32_16x16x32_bf16 v[8:11], v[154:157], v[218:221], v[8:11]
	v_mfma_f32_16x16x32_bf16 v[52:55], v[158:161], v[174:177], v[52:55]
	v_mfma_f32_16x16x32_bf16 v[48:51], v[166:169], v[174:177], v[48:51]
	v_mfma_f32_16x16x32_bf16 v[36:39], v[158:161], v[188:191], v[36:39]
	v_mfma_f32_16x16x32_bf16 v[32:35], v[166:169], v[188:191], v[32:35]
	v_mfma_f32_16x16x32_bf16 v[20:23], v[158:161], v[196:199], v[20:23]
	v_mfma_f32_16x16x32_bf16 v[16:19], v[166:169], v[196:199], v[16:19]
	v_mfma_f32_16x16x32_bf16 v[4:7], v[158:161], v[214:217], v[4:7]
	v_mfma_f32_16x16x32_bf16 v[0:3], v[166:169], v[214:217], v[0:3]
	v_mfma_f32_16x16x32_bf16 v[52:55], v[162:165], v[178:181], v[52:55]
	v_mfma_f32_16x16x32_bf16 v[48:51], v[170:173], v[178:181], v[48:51]
	v_mfma_f32_16x16x32_bf16 v[36:39], v[162:165], v[192:195], v[36:39]
	v_mfma_f32_16x16x32_bf16 v[32:35], v[170:173], v[192:195], v[32:35]
	v_mfma_f32_16x16x32_bf16 v[20:23], v[162:165], v[200:203], v[20:23]
	v_mfma_f32_16x16x32_bf16 v[16:19], v[170:173], v[200:203], v[16:19]
	v_mfma_f32_16x16x32_bf16 v[4:7], v[162:165], v[218:221], v[4:7]
	v_mfma_f32_16x16x32_bf16 v[0:3], v[170:173], v[218:221], v[0:3]
	s_barrier
	s_add_i32 s48, 0, 0x18000
	s_add_i32 s49, 0, 0x1c000
	v_add_u32_e32 v154, s48, v147
	v_add_u32_e32 v170, s49, v147
	ds_read_b128 v[138:141], v154
	ds_read_b128 v[142:145], v154 offset:1024
	ds_read_b128 v[150:153], v154 offset:2048
	ds_read_b128 v[154:157], v154 offset:3072
	ds_read_b128 v[158:161], v170
	ds_read_b128 v[162:165], v170 offset:1024
	ds_read_b128 v[166:169], v170 offset:2048
	ds_read_b128 v[170:173], v170 offset:3072
	s_add_u32 s20, s20, 0x80000
	s_addc_u32 s21, s21, 0
	s_mov_b32 m0, s28
	v_lshl_add_u64 v[228:229], s[20:21], 0, v[132:133]
	ds_read_b128 v[174:177], v149 offset:32768
	ds_read_b128 v[178:181], v149 offset:33792
	ds_read_b128 v[188:191], v149 offset:34816
	ds_read_b128 v[192:195], v149 offset:35840
	ds_read_b128 v[196:199], v149 offset:36864
	ds_read_b128 v[200:203], v149 offset:37888
	ds_read_b128 v[214:217], v149 offset:38912
	ds_read_b128 v[218:221], v149 offset:39936
	global_load_lds_dwordx4 v[228:229], off
	v_lshl_add_u64 v[228:229], s[20:21], 0, v[130:131]
	s_mov_b32 m0, s29
	s_nop 0
	global_load_lds_dwordx4 v[228:229], off
	s_waitcnt vmcnt(8)
	s_waitcnt lgkmcnt(0)
	s_barrier
	s_waitcnt lgkmcnt(0)
	v_mfma_f32_16x16x32_bf16 v[124:127], v[138:141], v[174:177], v[124:127]
	v_mfma_f32_16x16x32_bf16 v[120:123], v[150:153], v[174:177], v[120:123]
	v_mfma_f32_16x16x32_bf16 v[108:111], v[138:141], v[188:191], v[108:111]
	v_mfma_f32_16x16x32_bf16 v[104:107], v[150:153], v[188:191], v[104:107]
	v_mfma_f32_16x16x32_bf16 v[92:95], v[138:141], v[196:199], v[92:95]
	v_mfma_f32_16x16x32_bf16 v[88:91], v[150:153], v[196:199], v[88:91]
	v_mfma_f32_16x16x32_bf16 v[76:79], v[138:141], v[214:217], v[76:79]
	v_mfma_f32_16x16x32_bf16 v[72:75], v[150:153], v[214:217], v[72:75]
	v_mfma_f32_16x16x32_bf16 v[124:127], v[142:145], v[178:181], v[124:127]
	v_mfma_f32_16x16x32_bf16 v[120:123], v[154:157], v[178:181], v[120:123]
	v_mfma_f32_16x16x32_bf16 v[108:111], v[142:145], v[192:195], v[108:111]
	v_mfma_f32_16x16x32_bf16 v[104:107], v[154:157], v[192:195], v[104:107]
	v_mfma_f32_16x16x32_bf16 v[92:95], v[142:145], v[200:203], v[92:95]
	v_mfma_f32_16x16x32_bf16 v[88:91], v[154:157], v[200:203], v[88:91]
	v_mfma_f32_16x16x32_bf16 v[76:79], v[142:145], v[218:221], v[76:79]
	v_mfma_f32_16x16x32_bf16 v[72:75], v[154:157], v[218:221], v[72:75]
	v_mfma_f32_16x16x32_bf16 v[116:119], v[158:161], v[174:177], v[116:119]
	v_mfma_f32_16x16x32_bf16 v[112:115], v[166:169], v[174:177], v[112:115]
	v_mfma_f32_16x16x32_bf16 v[100:103], v[158:161], v[188:191], v[100:103]
	v_mfma_f32_16x16x32_bf16 v[96:99], v[166:169], v[188:191], v[96:99]
	v_mfma_f32_16x16x32_bf16 v[84:87], v[158:161], v[196:199], v[84:87]
	v_mfma_f32_16x16x32_bf16 v[80:83], v[166:169], v[196:199], v[80:83]
	v_mfma_f32_16x16x32_bf16 v[68:71], v[158:161], v[214:217], v[68:71]
	v_mfma_f32_16x16x32_bf16 v[64:67], v[166:169], v[214:217], v[64:67]
	v_mfma_f32_16x16x32_bf16 v[116:119], v[162:165], v[178:181], v[116:119]
	v_mfma_f32_16x16x32_bf16 v[112:115], v[170:173], v[178:181], v[112:115]
	v_mfma_f32_16x16x32_bf16 v[100:103], v[162:165], v[192:195], v[100:103]
	v_mfma_f32_16x16x32_bf16 v[96:99], v[170:173], v[192:195], v[96:99]
	v_mfma_f32_16x16x32_bf16 v[84:87], v[162:165], v[200:203], v[84:87]
	v_mfma_f32_16x16x32_bf16 v[80:83], v[170:173], v[200:203], v[80:83]
	v_mfma_f32_16x16x32_bf16 v[68:71], v[162:165], v[218:221], v[68:71]
	v_mfma_f32_16x16x32_bf16 v[64:67], v[170:173], v[218:221], v[64:67]
	s_barrier
; #define PG8_STAGE(bufoff, gbase, voff) do { _Pragma("unroll") for (int _i = 0; _i < 2; ++_i) \
;         __builtin_amdgcn_global_load_lds((const unsigned*)((const char*)(gbase) + (voff)[_i]), (PG8_LAS unsigned*)(lds + (bufoff) + ldsw + _i * 8192), 16, 0, 0); } while (0)
; #define PG8_LDA(dst, b, h) do { _Pragma("unroll") for (int m = 0; m < 4; ++m) _Pragma("unroll") for (int k = 0; k < 2; ++k) dst[m][k] = *(const PG8_LAS bf16x8*)(lds + PG8_SA(b, h) + aoff + m * 2048 + k * 1024); } while (0)
; #define PG8_MMA(ai, bj, At, Bt) do { __builtin_amdgcn_s_setprio(1); _Pragma("unroll") for (int m = 0; m < 4; ++m) _Pragma("unroll") for (int n = 0; n < 2; ++n) _Pragma("unroll") for (int k = 0; k < 2; ++k) \
;         acc[ai][bj][m][n] = __builtin_amdgcn_mfma_f32_16x16x32_bf16(Bt[n][k], At[m][k], acc[ai][bj][m][n], 0, 0, 0); __builtin_amdgcn_s_setprio(0); } while (0)
; #define PG8_WAIT_V(n) asm volatile("s_waitcnt vmcnt(" #n ")" ::: "memory")
; #define PG8_WAIT_L(n) asm volatile("s_waitcnt lgkmcnt(" #n ")" ::: "memory")
; #define PG8_BAR __builtin_amdgcn_s_barrier()
; #define PG8_SCHED __builtin_amdgcn_sched_barrier(0)
; template <class Epi, class Sched, bool ALIGN_EPI = false, bool SP2 = false>
; __device__ __forceinline__ void gemm_phase(PG8_LAS unsigned char* lds, const Gemm g, const Sched& S, const Epi& E, const int wid_in) {
;     ...
;         for (int t = 0; t < nt; t += 2) {
;             const bool last = (t == nt - 2);
;     ...
;             PG8_LDA(At, 1, 1); PG8_STAGE(PG8_SB(1, 0), b3, voffB); PG8_STAGE(PG8_SB(1, 1), b3 + hstep, voffB); PG8_STAGE(PG8_SA(1, 0), a3, voffA);
;             PG8_WAIT_V(8); PG8_WAIT_L(0); PG8_BAR; PG8_MMA(1, 0, At, B0); PG8_MMA(1, 1, At, B1); PG8_BAR; PG8_SCHED;
	s_add_i32 s20, s48, s25
	v_lshl_add_u64 v[204:205], v[204:205], 0, s[74:75]
	s_mov_b32 m0, s20
	ds_read_b128 v[174:177], v149 offset:49152
	ds_read_b128 v[178:181], v149 offset:50176
	ds_read_b128 v[188:191], v149 offset:51200
	ds_read_b128 v[192:195], v149 offset:52224
	ds_read_b128 v[196:199], v149 offset:53248
	ds_read_b128 v[200:203], v149 offset:54272
	ds_read_b128 v[214:217], v149 offset:55296
	ds_read_b128 v[218:221], v149 offset:56320
	global_load_lds_dwordx4 v[204:205], off
	s_add_i32 m0, s20, 0x2000
	s_add_u32 s18, s18, 0x80080
	v_lshl_add_u64 v[204:205], v[222:223], 0, s[74:75]
	s_addc_u32 s19, s19, 0
	s_add_i32 s20, s49, s25
	global_load_lds_dwordx4 v[204:205], off
	v_lshl_add_u64 v[204:205], s[18:19], 0, v[182:183]
	s_mov_b32 m0, s20
	s_nop 0
	global_load_lds_dwordx4 v[204:205], off
	v_lshl_add_u64 v[204:205], s[18:19], 0, v[128:129]
	s_add_i32 m0, s20, 0x2000
	s_nop 0
	global_load_lds_dwordx4 v[204:205], off
	v_lshl_add_u64 v[204:205], v[224:225], 0, s[74:75]
	s_mov_b32 m0, s36
	s_nop 0
	global_load_lds_dwordx4 v[204:205], off
	v_lshl_add_u64 v[204:205], v[226:227], 0, s[74:75]
	s_mov_b32 m0, s37
	s_nop 0
	global_load_lds_dwordx4 v[204:205], off
	s_waitcnt vmcnt(8)
	s_waitcnt lgkmcnt(0)
	s_barrier
	s_waitcnt lgkmcnt(0)
	v_mfma_f32_16x16x32_bf16 v[60:63], v[138:141], v[174:177], v[60:63]
	v_mfma_f32_16x16x32_bf16 v[56:59], v[150:153], v[174:177], v[56:59]
	v_mfma_f32_16x16x32_bf16 v[44:47], v[138:141], v[188:191], v[44:47]
	v_mfma_f32_16x16x32_bf16 v[40:43], v[150:153], v[188:191], v[40:43]
	v_mfma_f32_16x16x32_bf16 v[28:31], v[138:141], v[196:199], v[28:31]
	v_mfma_f32_16x16x32_bf16 v[24:27], v[150:153], v[196:199], v[24:27]
	v_mfma_f32_16x16x32_bf16 v[12:15], v[138:141], v[214:217], v[12:15]
	v_mfma_f32_16x16x32_bf16 v[8:11], v[150:153], v[214:217], v[8:11]
	v_mfma_f32_16x16x32_bf16 v[60:63], v[142:145], v[178:181], v[60:63]
	v_mfma_f32_16x16x32_bf16 v[56:59], v[154:157], v[178:181], v[56:59]
	v_mfma_f32_16x16x32_bf16 v[44:47], v[142:145], v[192:195], v[44:47]
	v_mfma_f32_16x16x32_bf16 v[40:43], v[154:157], v[192:195], v[40:43]
	v_mfma_f32_16x16x32_bf16 v[28:31], v[142:145], v[200:203], v[28:31]
	v_mfma_f32_16x16x32_bf16 v[24:27], v[154:157], v[200:203], v[24:27]
	v_mfma_f32_16x16x32_bf16 v[12:15], v[142:145], v[218:221], v[12:15]
	v_mfma_f32_16x16x32_bf16 v[8:11], v[154:157], v[218:221], v[8:11]
	v_mfma_f32_16x16x32_bf16 v[52:55], v[158:161], v[174:177], v[52:55]
	v_mfma_f32_16x16x32_bf16 v[48:51], v[166:169], v[174:177], v[48:51]
	v_mfma_f32_16x16x32_bf16 v[36:39], v[158:161], v[188:191], v[36:39]
	v_mfma_f32_16x16x32_bf16 v[32:35], v[166:169], v[188:191], v[32:35]
	v_mfma_f32_16x16x32_bf16 v[20:23], v[158:161], v[196:199], v[20:23]
	v_mfma_f32_16x16x32_bf16 v[16:19], v[166:169], v[196:199], v[16:19]
	v_mfma_f32_16x16x32_bf16 v[4:7], v[158:161], v[214:217], v[4:7]
	v_mfma_f32_16x16x32_bf16 v[0:3], v[166:169], v[214:217], v[0:3]
	v_mfma_f32_16x16x32_bf16 v[52:55], v[162:165], v[178:181], v[52:55]
	v_mfma_f32_16x16x32_bf16 v[48:51], v[170:173], v[178:181], v[48:51]
	v_mfma_f32_16x16x32_bf16 v[36:39], v[162:165], v[192:195], v[36:39]
	v_mfma_f32_16x16x32_bf16 v[32:35], v[170:173], v[192:195], v[32:35]
	v_mfma_f32_16x16x32_bf16 v[20:23], v[162:165], v[200:203], v[20:23]
	v_mfma_f32_16x16x32_bf16 v[16:19], v[170:173], v[200:203], v[16:19]
	v_mfma_f32_16x16x32_bf16 v[4:7], v[162:165], v[218:221], v[4:7]
	v_mfma_f32_16x16x32_bf16 v[0:3], v[170:173], v[218:221], v[0:3]
	s_barrier
	s_add_i32 s47, s47, 2
	s_add_u32 s4, s4, 0x100
	s_addc_u32 s5, s5, 0
	s_add_u32 s45, s45, 0x100
	s_addc_u32 s46, s46, 0
	s_cmp_gt_u32 s47, 29
	s_cbranch_scc0 .LBB0_1212
	s_and_b64 vcc, exec, s[8:9]
	s_cbranch_vccz .LBB0_1215
	s_barrier

; #define PG8_STAGE(bufoff, gbase, voff) do { _Pragma("unroll") for (int _i = 0; _i < 2; ++_i) \
;         __builtin_amdgcn_global_load_lds((const unsigned*)((const char*)(gbase) + (voff)[_i]), (PG8_LAS unsigned*)(lds + (bufoff) + ldsw + _i * 8192), 16, 0, 0); } while (0)
; #define PG8_LDA(dst, b, h) do { _Pragma("unroll") for (int m = 0; m < 4; ++m) _Pragma("unroll") for (int k = 0; k < 2; ++k) dst[m][k] = *(const PG8_LAS bf16x8*)(lds + PG8_SA(b, h) + aoff + m * 2048 + k * 1024); } while (0)
; #define PG8_LDB(dst, b, h) do { _Pragma("unroll") for (int n = 0; n < 2; ++n) _Pragma("unroll") for (int k = 0; k < 2; ++k) dst[n][k] = *(const PG8_LAS bf16x8*)(lds + PG8_SB(b, h) + boff + n * 2048 + k * 1024); } while (0)
; #define PG8_MMA(ai, bj, At, Bt) do { __builtin_amdgcn_s_setprio(1); _Pragma("unroll") for (int m = 0; m < 4; ++m) _Pragma("unroll") for (int n = 0; n < 2; ++n) _Pragma("unroll") for (int k = 0; k < 2; ++k) \
;         acc[ai][bj][m][n] = __builtin_amdgcn_mfma_f32_16x16x32_bf16(Bt[n][k], At[m][k], acc[ai][bj][m][n], 0, 0, 0); __builtin_amdgcn_s_setprio(0); } while (0)
; #define PG8_WAIT_V(n) asm volatile("s_waitcnt vmcnt(" #n ")" ::: "memory")
; #define PG8_WAIT_L(n) asm volatile("s_waitcnt lgkmcnt(" #n ")" ::: "memory")
; #define PG8_BAR __builtin_amdgcn_s_barrier()
; #define PG8_SCHED __builtin_amdgcn_sched_barrier(0)
; template <class Epi, class Sched, bool ALIGN_EPI = false, bool SP2 = false>
; __device__ __forceinline__ void gemm_phase(PG8_LAS unsigned char* lds, const Gemm g, const Sched& S, const Epi& E, const int wid_in) {
;     ...
;             PG8_LDB(B0, 0, 0); PG8_LDB(B1, 0, 1); PG8_SCHED; PG8_LDA(At, 0, 0); PG8_STAGE(PG8_SA(1, 1), a1 + hstep, voffA);
;             PG8_WAIT_V(8); PG8_WAIT_L(0); PG8_BAR; PG8_MMA(0, 0, At, B0); PG8_MMA(0, 1, At, B1); PG8_BAR; PG8_SCHED;
;             PG8_LDA(At, 0, 1); PG8_STAGE(PG8_SB(0, 0), b2, voffB); PG8_STAGE(PG8_SB(0, 1), b2 + hstep, voffB); PG8_STAGE(PG8_SA(0, 0), a2, voffA);
;             PG8_WAIT_V(8); PG8_WAIT_L(0); PG8_BAR; PG8_MMA(1, 0, At, B0); PG8_MMA(1, 1, At, B1); PG8_BAR; PG8_SCHED;
.LBB0_1269:
	s_add_u32 s24, s4, 0x100
	s_addc_u32 s25, s5, 0
	s_add_i32 s54, 0, 0x10000
	s_cmpk_eq_i32 s53, 0x7c
	s_cselect_b32 s29, s19, s25
	s_cselect_b32 s28, s49, s24
	s_cselect_b32 s27, s17, s52
	s_cselect_b32 s26, s50, s51
	s_add_i32 s55, 0, 0x14000
	v_add_u32_e32 v88, s54, v215
	v_add_u32_e32 v156, s55, v215
	ds_read_b128 v[72:75], v88
	ds_read_b128 v[80:83], v88 offset:1024
	ds_read_b128 v[84:87], v88 offset:2048
	ds_read_b128 v[88:91], v88 offset:3072
	ds_read_b128 v[144:147], v156
	ds_read_b128 v[148:151], v156 offset:1024
	ds_read_b128 v[152:155], v156 offset:2048
	ds_read_b128 v[156:159], v156 offset:3072
	v_lshl_add_u64 v[180:181], s[4:5], 0, v[192:193]
	s_add_i32 m0, s40, 0xc000
	ds_read_b128 v[160:163], v219
	ds_read_b128 v[164:167], v219 offset:1024
	ds_read_b128 v[168:171], v219 offset:2048
	ds_read_b128 v[172:175], v219 offset:3072
	ds_read_b128 v[176:179], v219 offset:4096
	ds_read_b128 v[196:199], v219 offset:5120
	ds_read_b128 v[200:203], v219 offset:6144
	ds_read_b128 v[220:223], v219 offset:7168
	global_load_lds_dwordx4 v[180:181], off
	v_lshl_add_u64 v[180:181], s[4:5], 0, v[194:195]
	s_add_i32 m0, s40, 0xe000
	s_nop 0
	global_load_lds_dwordx4 v[180:181], off
	s_waitcnt vmcnt(8)
	s_waitcnt lgkmcnt(0)
	s_barrier
	s_waitcnt lgkmcnt(0)
	v_mfma_f32_16x16x32_bf16 v[140:143], v[72:75], v[160:163], v[140:143]
	v_mfma_f32_16x16x32_bf16 v[136:139], v[84:87], v[160:163], v[136:139]
	v_mfma_f32_16x16x32_bf16 v[128:131], v[72:75], v[168:171], v[128:131]
	v_mfma_f32_16x16x32_bf16 v[120:123], v[84:87], v[168:171], v[120:123]
	v_mfma_f32_16x16x32_bf16 v[112:115], v[72:75], v[176:179], v[112:115]
	v_mfma_f32_16x16x32_bf16 v[104:107], v[84:87], v[176:179], v[104:107]
	v_mfma_f32_16x16x32_bf16 v[96:99], v[72:75], v[200:203], v[96:99]
	v_mfma_f32_16x16x32_bf16 v[76:79], v[84:87], v[200:203], v[76:79]
	v_mfma_f32_16x16x32_bf16 v[140:143], v[80:83], v[164:167], v[140:143]
	v_mfma_f32_16x16x32_bf16 v[136:139], v[88:91], v[164:167], v[136:139]
	v_mfma_f32_16x16x32_bf16 v[128:131], v[80:83], v[172:175], v[128:131]
	v_mfma_f32_16x16x32_bf16 v[120:123], v[88:91], v[172:175], v[120:123]
	v_mfma_f32_16x16x32_bf16 v[112:115], v[80:83], v[196:199], v[112:115]
	v_mfma_f32_16x16x32_bf16 v[104:107], v[88:91], v[196:199], v[104:107]
	v_mfma_f32_16x16x32_bf16 v[96:99], v[80:83], v[220:223], v[96:99]
	v_mfma_f32_16x16x32_bf16 v[76:79], v[88:91], v[220:223], v[76:79]
	v_mfma_f32_16x16x32_bf16 v[132:135], v[144:147], v[160:163], v[132:135]
	v_mfma_f32_16x16x32_bf16 v[124:127], v[152:155], v[160:163], v[124:127]
	v_mfma_f32_16x16x32_bf16 v[116:119], v[144:147], v[168:171], v[116:119]
	v_mfma_f32_16x16x32_bf16 v[108:111], v[152:155], v[168:171], v[108:111]
	v_mfma_f32_16x16x32_bf16 v[100:103], v[144:147], v[176:179], v[100:103]
	v_mfma_f32_16x16x32_bf16 v[92:95], v[152:155], v[176:179], v[92:95]
	v_mfma_f32_16x16x32_bf16 v[68:71], v[144:147], v[200:203], v[68:71]
	v_mfma_f32_16x16x32_bf16 v[64:67], v[152:155], v[200:203], v[64:67]
	v_mfma_f32_16x16x32_bf16 v[132:135], v[148:151], v[164:167], v[132:135]
	v_mfma_f32_16x16x32_bf16 v[124:127], v[156:159], v[164:167], v[124:127]
	v_mfma_f32_16x16x32_bf16 v[116:119], v[148:151], v[172:175], v[116:119]
	v_mfma_f32_16x16x32_bf16 v[108:111], v[156:159], v[172:175], v[108:111]
	v_mfma_f32_16x16x32_bf16 v[100:103], v[148:151], v[196:199], v[100:103]
	v_mfma_f32_16x16x32_bf16 v[92:95], v[156:159], v[196:199], v[92:95]
	v_mfma_f32_16x16x32_bf16 v[68:71], v[148:151], v[220:223], v[68:71]
	v_mfma_f32_16x16x32_bf16 v[64:67], v[156:159], v[220:223], v[64:67]
	s_barrier
	s_add_i32 s4, s54, s39
	v_lshl_add_u64 v[180:181], s[26:27], 0, v[182:183]
	s_mov_b32 m0, s4
	ds_read_b128 v[160:163], v219 offset:16384
	ds_read_b128 v[164:167], v219 offset:17408
	ds_read_b128 v[168:171], v219 offset:18432
	ds_read_b128 v[172:175], v219 offset:19456
	ds_read_b128 v[176:179], v219 offset:20480
	ds_read_b128 v[196:199], v219 offset:21504
	ds_read_b128 v[200:203], v219 offset:22528
	ds_read_b128 v[220:223], v219 offset:23552
	global_load_lds_dwordx4 v[180:181], off
	s_add_i32 m0, s4, 0x2000
	s_add_u32 s4, s26, 0x200000
	v_lshl_add_u64 v[188:189], s[26:27], 0, v[190:191]
	s_addc_u32 s5, s27, 0
	s_add_i32 s54, s55, s39
	global_load_lds_dwordx4 v[188:189], off
	v_lshl_add_u64 v[204:205], s[4:5], 0, v[182:183]
	s_mov_b32 m0, s54
	v_lshl_add_u64 v[224:225], s[28:29], 0, v[190:191]
	global_load_lds_dwordx4 v[204:205], off
	v_lshl_add_u64 v[204:205], s[4:5], 0, v[190:191]
	s_add_i32 m0, s54, 0x2000
	s_nop 0
	global_load_lds_dwordx4 v[204:205], off
	v_lshl_add_u64 v[204:205], s[28:29], 0, v[182:183]
	s_mov_b32 m0, s40
	s_nop 0
	global_load_lds_dwordx4 v[204:205], off
	s_mov_b32 m0, s41
	s_nop 0
	global_load_lds_dwordx4 v[224:225], off
	s_waitcnt vmcnt(8)
	s_waitcnt lgkmcnt(0)
	s_barrier
; #define PG8_STAGE(bufoff, gbase, voff) do { _Pragma("unroll") for (int _i = 0; _i < 2; ++_i) \
;         __builtin_amdgcn_global_load_lds((const unsigned*)((const char*)(gbase) + (voff)[_i]), (PG8_LAS unsigned*)(lds + (bufoff) + ldsw + _i * 8192), 16, 0, 0); } while (0)
; #define PG8_LDA(dst, b, h) do { _Pragma("unroll") for (int m = 0; m < 4; ++m) _Pragma("unroll") for (int k = 0; k < 2; ++k) dst[m][k] = *(const PG8_LAS bf16x8*)(lds + PG8_SA(b, h) + aoff + m * 2048 + k * 1024); } while (0)
; #define PG8_LDB(dst, b, h) do { _Pragma("unroll") for (int n = 0; n < 2; ++n) _Pragma("unroll") for (int k = 0; k < 2; ++k) dst[n][k] = *(const PG8_LAS bf16x8*)(lds + PG8_SB(b, h) + boff + n * 2048 + k * 1024); } while (0)
; #define PG8_MMA(ai, bj, At, Bt) do { __builtin_amdgcn_s_setprio(1); _Pragma("unroll") for (int m = 0; m < 4; ++m) _Pragma("unroll") for (int n = 0; n < 2; ++n) _Pragma("unroll") for (int k = 0; k < 2; ++k) \
;         acc[ai][bj][m][n] = __builtin_amdgcn_mfma_f32_16x16x32_bf16(Bt[n][k], At[m][k], acc[ai][bj][m][n], 0, 0, 0); __builtin_amdgcn_s_setprio(0); } while (0)
; #define PG8_WAIT_V(n) asm volatile("s_waitcnt vmcnt(" #n ")" ::: "memory")
; #define PG8_WAIT_L(n) asm volatile("s_waitcnt lgkmcnt(" #n ")" ::: "memory")
; #define PG8_BAR __builtin_amdgcn_s_barrier()
; #define PG8_SCHED __builtin_amdgcn_sched_barrier(0)
; template <class Epi, class Sched, bool ALIGN_EPI = false, bool SP2 = false>
; __device__ __forceinline__ void gemm_phase(PG8_LAS unsigned char* lds, const Gemm g, const Sched& S, const Epi& E, const int wid_in) {
;     ...
;             PG8_WAIT_V(8); PG8_WAIT_L(0); PG8_BAR; PG8_MMA(1, 0, At, B0); PG8_MMA(1, 1, At, B1); PG8_BAR; PG8_SCHED;
;             PG8_LDB(B0, 1, 0); PG8_LDB(B1, 1, 1); PG8_SCHED; PG8_LDA(At, 1, 0); PG8_STAGE(PG8_SA(0, 1), a2 + hstep, voffA);
;             PG8_WAIT_V(8); PG8_WAIT_L(0); PG8_BAR; PG8_MMA(0, 0, At, B0); PG8_MMA(0, 1, At, B1); PG8_BAR; PG8_SCHED;
	s_waitcnt lgkmcnt(0)
	v_mfma_f32_16x16x32_bf16 v[60:63], v[72:75], v[160:163], v[60:63]
	v_mfma_f32_16x16x32_bf16 v[56:59], v[84:87], v[160:163], v[56:59]
	v_mfma_f32_16x16x32_bf16 v[48:51], v[72:75], v[168:171], v[48:51]
	v_mfma_f32_16x16x32_bf16 v[40:43], v[84:87], v[168:171], v[40:43]
	v_mfma_f32_16x16x32_bf16 v[32:35], v[72:75], v[176:179], v[32:35]
	v_mfma_f32_16x16x32_bf16 v[24:27], v[84:87], v[176:179], v[24:27]
	v_mfma_f32_16x16x32_bf16 v[20:23], v[72:75], v[200:203], v[20:23]
	v_mfma_f32_16x16x32_bf16 v[8:11], v[84:87], v[200:203], v[8:11]
	v_mfma_f32_16x16x32_bf16 v[60:63], v[80:83], v[164:167], v[60:63]
	v_mfma_f32_16x16x32_bf16 v[56:59], v[88:91], v[164:167], v[56:59]
	v_mfma_f32_16x16x32_bf16 v[48:51], v[80:83], v[172:175], v[48:51]
	v_mfma_f32_16x16x32_bf16 v[40:43], v[88:91], v[172:175], v[40:43]
	v_mfma_f32_16x16x32_bf16 v[32:35], v[80:83], v[196:199], v[32:35]
	v_mfma_f32_16x16x32_bf16 v[24:27], v[88:91], v[196:199], v[24:27]
	v_mfma_f32_16x16x32_bf16 v[20:23], v[80:83], v[220:223], v[20:23]
	v_mfma_f32_16x16x32_bf16 v[8:11], v[88:91], v[220:223], v[8:11]
	v_mfma_f32_16x16x32_bf16 v[52:55], v[144:147], v[160:163], v[52:55]
	v_mfma_f32_16x16x32_bf16 v[44:47], v[152:155], v[160:163], v[44:47]
	v_mfma_f32_16x16x32_bf16 v[36:39], v[144:147], v[168:171], v[36:39]
	v_mfma_f32_16x16x32_bf16 v[28:31], v[152:155], v[168:171], v[28:31]
	v_mfma_f32_16x16x32_bf16 v[16:19], v[144:147], v[176:179], v[16:19]
	v_mfma_f32_16x16x32_bf16 v[12:15], v[152:155], v[176:179], v[12:15]
	v_mfma_f32_16x16x32_bf16 v[4:7], v[144:147], v[200:203], v[4:7]
	v_mfma_f32_16x16x32_bf16 v[0:3], v[152:155], v[200:203], v[0:3]
	v_mfma_f32_16x16x32_bf16 v[52:55], v[148:151], v[164:167], v[52:55]
	v_mfma_f32_16x16x32_bf16 v[44:47], v[156:159], v[164:167], v[44:47]
	v_mfma_f32_16x16x32_bf16 v[36:39], v[148:151], v[172:175], v[36:39]
	v_mfma_f32_16x16x32_bf16 v[28:31], v[156:159], v[172:175], v[28:31]
	v_mfma_f32_16x16x32_bf16 v[16:19], v[148:151], v[196:199], v[16:19]
	v_mfma_f32_16x16x32_bf16 v[12:15], v[156:159], v[196:199], v[12:15]
	v_mfma_f32_16x16x32_bf16 v[4:7], v[148:151], v[220:223], v[4:7]
	v_mfma_f32_16x16x32_bf16 v[0:3], v[156:159], v[220:223], v[0:3]
	s_barrier
	s_add_i32 s54, 0, 0x18000
	s_add_i32 s55, 0, 0x1c000
	v_add_u32_e32 v88, s54, v215
	v_add_u32_e32 v156, s55, v215
	ds_read_b128 v[72:75], v88
	ds_read_b128 v[80:83], v88 offset:1024
	ds_read_b128 v[84:87], v88 offset:2048
	ds_read_b128 v[88:91], v88 offset:3072
	ds_read_b128 v[144:147], v156
	ds_read_b128 v[148:151], v156 offset:1024
	ds_read_b128 v[152:155], v156 offset:2048
	ds_read_b128 v[156:159], v156 offset:3072
	s_add_u32 s4, s28, 0x200000
	s_addc_u32 s5, s29, 0
	s_mov_b32 m0, s42
	v_lshl_add_u64 v[226:227], s[4:5], 0, v[182:183]
	ds_read_b128 v[160:163], v219 offset:32768
	ds_read_b128 v[164:167], v219 offset:33792
	ds_read_b128 v[168:171], v219 offset:34816
	ds_read_b128 v[172:175], v219 offset:35840
	ds_read_b128 v[176:179], v219 offset:36864
	ds_read_b128 v[196:199], v219 offset:37888
	ds_read_b128 v[200:203], v219 offset:38912
	ds_read_b128 v[220:223], v219 offset:39936
	global_load_lds_dwordx4 v[226:227], off
	v_lshl_add_u64 v[226:227], s[4:5], 0, v[190:191]
	s_mov_b32 m0, s43
	s_nop 0
	global_load_lds_dwordx4 v[226:227], off
	s_waitcnt vmcnt(8)
	s_waitcnt lgkmcnt(0)
	s_barrier
	s_waitcnt lgkmcnt(0)
	v_mfma_f32_16x16x32_bf16 v[140:143], v[72:75], v[160:163], v[140:143]
	v_mfma_f32_16x16x32_bf16 v[136:139], v[84:87], v[160:163], v[136:139]
	v_mfma_f32_16x16x32_bf16 v[128:131], v[72:75], v[168:171], v[128:131]
	v_mfma_f32_16x16x32_bf16 v[120:123], v[84:87], v[168:171], v[120:123]
	v_mfma_f32_16x16x32_bf16 v[112:115], v[72:75], v[176:179], v[112:115]
	v_mfma_f32_16x16x32_bf16 v[104:107], v[84:87], v[176:179], v[104:107]
	v_mfma_f32_16x16x32_bf16 v[96:99], v[72:75], v[200:203], v[96:99]
	v_mfma_f32_16x16x32_bf16 v[76:79], v[84:87], v[200:203], v[76:79]
	v_mfma_f32_16x16x32_bf16 v[140:143], v[80:83], v[164:167], v[140:143]
	v_mfma_f32_16x16x32_bf16 v[136:139], v[88:91], v[164:167], v[136:139]
	v_mfma_f32_16x16x32_bf16 v[128:131], v[80:83], v[172:175], v[128:131]
	v_mfma_f32_16x16x32_bf16 v[120:123], v[88:91], v[172:175], v[120:123]
	v_mfma_f32_16x16x32_bf16 v[112:115], v[80:83], v[196:199], v[112:115]
	v_mfma_f32_16x16x32_bf16 v[104:107], v[88:91], v[196:199], v[104:107]
	v_mfma_f32_16x16x32_bf16 v[96:99], v[80:83], v[220:223], v[96:99]
	v_mfma_f32_16x16x32_bf16 v[76:79], v[88:91], v[220:223], v[76:79]
	v_mfma_f32_16x16x32_bf16 v[132:135], v[144:147], v[160:163], v[132:135]
	v_mfma_f32_16x16x32_bf16 v[124:127], v[152:155], v[160:163], v[124:127]
	v_mfma_f32_16x16x32_bf16 v[116:119], v[144:147], v[168:171], v[116:119]
	v_mfma_f32_16x16x32_bf16 v[108:111], v[152:155], v[168:171], v[108:111]
	v_mfma_f32_16x16x32_bf16 v[100:103], v[144:147], v[176:179], v[100:103]
	v_mfma_f32_16x16x32_bf16 v[92:95], v[152:155], v[176:179], v[92:95]
	v_mfma_f32_16x16x32_bf16 v[68:71], v[144:147], v[200:203], v[68:71]
	v_mfma_f32_16x16x32_bf16 v[64:67], v[152:155], v[200:203], v[64:67]
	v_mfma_f32_16x16x32_bf16 v[132:135], v[148:151], v[164:167], v[132:135]
	v_mfma_f32_16x16x32_bf16 v[124:127], v[156:159], v[164:167], v[124:127]
	v_mfma_f32_16x16x32_bf16 v[116:119], v[148:151], v[172:175], v[116:119]
	v_mfma_f32_16x16x32_bf16 v[108:111], v[156:159], v[172:175], v[108:111]
	v_mfma_f32_16x16x32_bf16 v[100:103], v[148:151], v[196:199], v[100:103]
	v_mfma_f32_16x16x32_bf16 v[92:95], v[156:159], v[196:199], v[92:95]
	v_mfma_f32_16x16x32_bf16 v[68:71], v[148:151], v[220:223], v[68:71]
	v_mfma_f32_16x16x32_bf16 v[64:67], v[156:159], v[220:223], v[64:67]
	s_barrier
; #define PG8_STAGE(bufoff, gbase, voff) do { _Pragma("unroll") for (int _i = 0; _i < 2; ++_i) \
;         __builtin_amdgcn_global_load_lds((const unsigned*)((const char*)(gbase) + (voff)[_i]), (PG8_LAS unsigned*)(lds + (bufoff) + ldsw + _i * 8192), 16, 0, 0); } while (0)
; #define PG8_LDA(dst, b, h) do { _Pragma("unroll") for (int m = 0; m < 4; ++m) _Pragma("unroll") for (int k = 0; k < 2; ++k) dst[m][k] = *(const PG8_LAS bf16x8*)(lds + PG8_SA(b, h) + aoff + m * 2048 + k * 1024); } while (0)
; #define PG8_MMA(ai, bj, At, Bt) do { __builtin_amdgcn_s_setprio(1); _Pragma("unroll") for (int m = 0; m < 4; ++m) _Pragma("unroll") for (int n = 0; n < 2; ++n) _Pragma("unroll") for (int k = 0; k < 2; ++k) \
;         acc[ai][bj][m][n] = __builtin_amdgcn_mfma_f32_16x16x32_bf16(Bt[n][k], At[m][k], acc[ai][bj][m][n], 0, 0, 0); __builtin_amdgcn_s_setprio(0); } while (0)
; #define PG8_WAIT_V(n) asm volatile("s_waitcnt vmcnt(" #n ")" ::: "memory")
; #define PG8_WAIT_L(n) asm volatile("s_waitcnt lgkmcnt(" #n ")" ::: "memory")
; #define PG8_BAR __builtin_amdgcn_s_barrier()
; #define PG8_SCHED __builtin_amdgcn_sched_barrier(0)
; template <class Epi, class Sched, bool ALIGN_EPI = false, bool SP2 = false>
; __device__ __forceinline__ void gemm_phase(PG8_LAS unsigned char* lds, const Gemm g, const Sched& S, const Epi& E, const int wid_in) {
;     ...
;         for (int t = 0; t < nt; t += 2) {
;             const bool last = (t == nt - 2);
;     ...
;             PG8_LDA(At, 1, 1); PG8_STAGE(PG8_SB(1, 0), b3, voffB); PG8_STAGE(PG8_SB(1, 1), b3 + hstep, voffB); PG8_STAGE(PG8_SA(1, 0), a3, voffA);
;             PG8_WAIT_V(8); PG8_WAIT_L(0); PG8_BAR; PG8_MMA(1, 0, At, B0); PG8_MMA(1, 1, At, B1); PG8_BAR; PG8_SCHED;
	s_add_i32 s4, s54, s39
	v_lshl_add_u64 v[180:181], v[180:181], 0, s[74:75]
	s_mov_b32 m0, s4
	ds_read_b128 v[160:163], v219 offset:49152
	ds_read_b128 v[164:167], v219 offset:50176
	ds_read_b128 v[168:171], v219 offset:51200
	ds_read_b128 v[172:175], v219 offset:52224
	ds_read_b128 v[176:179], v219 offset:53248
	ds_read_b128 v[196:199], v219 offset:54272
	ds_read_b128 v[200:203], v219 offset:55296
	ds_read_b128 v[220:223], v219 offset:56320
	global_load_lds_dwordx4 v[180:181], off
	s_add_i32 m0, s4, 0x2000
	s_add_u32 s4, s26, 0x200080
	v_lshl_add_u64 v[180:181], v[188:189], 0, s[74:75]
	s_addc_u32 s5, s27, 0
	s_add_i32 s26, s55, s39
	global_load_lds_dwordx4 v[180:181], off
	v_lshl_add_u64 v[180:181], s[4:5], 0, v[182:183]
	s_mov_b32 m0, s26
	s_nop 0
	global_load_lds_dwordx4 v[180:181], off
	v_lshl_add_u64 v[180:181], s[4:5], 0, v[190:191]
	s_add_i32 m0, s26, 0x2000
	s_nop 0
	global_load_lds_dwordx4 v[180:181], off
	v_lshl_add_u64 v[180:181], v[204:205], 0, s[74:75]
	s_mov_b32 m0, s45
	s_nop 0
	global_load_lds_dwordx4 v[180:181], off
	v_lshl_add_u64 v[180:181], v[224:225], 0, s[74:75]
	s_mov_b32 m0, s46
	s_nop 0
	global_load_lds_dwordx4 v[180:181], off
	s_waitcnt vmcnt(8)
	s_waitcnt lgkmcnt(0)
	s_barrier
	s_waitcnt lgkmcnt(0)
	v_mfma_f32_16x16x32_bf16 v[60:63], v[72:75], v[160:163], v[60:63]
	v_mfma_f32_16x16x32_bf16 v[56:59], v[84:87], v[160:163], v[56:59]
	v_mfma_f32_16x16x32_bf16 v[48:51], v[72:75], v[168:171], v[48:51]
	v_mfma_f32_16x16x32_bf16 v[40:43], v[84:87], v[168:171], v[40:43]
	v_mfma_f32_16x16x32_bf16 v[32:35], v[72:75], v[176:179], v[32:35]
	v_mfma_f32_16x16x32_bf16 v[24:27], v[84:87], v[176:179], v[24:27]
	v_mfma_f32_16x16x32_bf16 v[20:23], v[72:75], v[200:203], v[20:23]
	v_mfma_f32_16x16x32_bf16 v[8:11], v[84:87], v[200:203], v[8:11]
	v_mfma_f32_16x16x32_bf16 v[60:63], v[80:83], v[164:167], v[60:63]
	v_mfma_f32_16x16x32_bf16 v[56:59], v[88:91], v[164:167], v[56:59]
	v_mfma_f32_16x16x32_bf16 v[48:51], v[80:83], v[172:175], v[48:51]
	v_mfma_f32_16x16x32_bf16 v[40:43], v[88:91], v[172:175], v[40:43]
	v_mfma_f32_16x16x32_bf16 v[32:35], v[80:83], v[196:199], v[32:35]
	v_mfma_f32_16x16x32_bf16 v[24:27], v[88:91], v[196:199], v[24:27]
	v_mfma_f32_16x16x32_bf16 v[20:23], v[80:83], v[220:223], v[20:23]
	v_mfma_f32_16x16x32_bf16 v[8:11], v[88:91], v[220:223], v[8:11]
	v_mfma_f32_16x16x32_bf16 v[52:55], v[144:147], v[160:163], v[52:55]
	v_mfma_f32_16x16x32_bf16 v[44:47], v[152:155], v[160:163], v[44:47]
	v_mfma_f32_16x16x32_bf16 v[36:39], v[144:147], v[168:171], v[36:39]
	v_mfma_f32_16x16x32_bf16 v[28:31], v[152:155], v[168:171], v[28:31]
	v_mfma_f32_16x16x32_bf16 v[16:19], v[144:147], v[176:179], v[16:19]
	v_mfma_f32_16x16x32_bf16 v[12:15], v[152:155], v[176:179], v[12:15]
	v_mfma_f32_16x16x32_bf16 v[4:7], v[144:147], v[200:203], v[4:7]
	v_mfma_f32_16x16x32_bf16 v[0:3], v[152:155], v[200:203], v[0:3]
	v_mfma_f32_16x16x32_bf16 v[52:55], v[148:151], v[164:167], v[52:55]
	v_mfma_f32_16x16x32_bf16 v[44:47], v[156:159], v[164:167], v[44:47]
	v_mfma_f32_16x16x32_bf16 v[36:39], v[148:151], v[172:175], v[36:39]
	v_mfma_f32_16x16x32_bf16 v[28:31], v[156:159], v[172:175], v[28:31]
	v_mfma_f32_16x16x32_bf16 v[16:19], v[148:151], v[196:199], v[16:19]
	v_mfma_f32_16x16x32_bf16 v[12:15], v[156:159], v[196:199], v[12:15]
	v_mfma_f32_16x16x32_bf16 v[4:7], v[148:151], v[220:223], v[4:7]
	v_mfma_f32_16x16x32_bf16 v[0:3], v[156:159], v[220:223], v[0:3]
	s_barrier
	s_add_i32 s53, s53, 2
	s_add_u32 s51, s51, 0x100
	s_addc_u32 s52, s52, 0
	s_cmpk_gt_u32 s53, 0x7d
	s_mov_b64 s[4:5], s[24:25]
	s_cbranch_scc0 .LBB0_1269
	s_and_b64 vcc, exec, s[14:15]
	s_cbranch_vccz .LBB0_1272
	s_barrier
